# v11 + SGPR-base LDS-DMA loads (no 64-bit VALU address adds) in the down-proj and in-proj GEMM K-loops
# speedup vs baseline: 1.0132x; 1.0002x over previous
; #define PG8_STAGE(bufoff, gbase, voff) do { _Pragma("unroll") for (int _i = 0; _i < 2; ++_i) \
;         __builtin_amdgcn_global_load_lds((const unsigned*)((const char*)(gbase) + (voff)[_i]), (PG8_LAS unsigned*)(lds + (bufoff) + ldsw + _i * 8192), 16, 0, 0); } while (0)
; #define PG8_LDA(dst, b, h) do { _Pragma("unroll") for (int m = 0; m < 4; ++m) _Pragma("unroll") for (int k = 0; k < 2; ++k) dst[m][k] = *(const PG8_LAS bf16x8*)(lds + PG8_SA(b, h) + aoff + m * 2048 + k * 1024); } while (0)
; #define PG8_LDB(dst, b, h) do { _Pragma("unroll") for (int n = 0; n < 2; ++n) _Pragma("unroll") for (int k = 0; k < 2; ++k) dst[n][k] = *(const PG8_LAS bf16x8*)(lds + PG8_SB(b, h) + boff + n * 2048 + k * 1024); } while (0)
; #define PG8_MMA(ai, bj, At, Bt) do { __builtin_amdgcn_s_setprio(1); _Pragma("unroll") for (int m = 0; m < 4; ++m) _Pragma("unroll") for (int n = 0; n < 2; ++n) _Pragma("unroll") for (int k = 0; k < 2; ++k) \
;         acc[ai][bj][m][n] = __builtin_amdgcn_mfma_f32_16x16x32_bf16(Bt[n][k], At[m][k], acc[ai][bj][m][n], 0, 0, 0); __builtin_amdgcn_s_setprio(0); } while (0)
; #define PG8_BAR __builtin_amdgcn_s_barrier()
; template <class Epi, class Sched, bool ALIGN_EPI = false, bool SP2 = false>
; __device__ __forceinline__ void gemm_phase(PG8_LAS unsigned char* lds, const Gemm g, const Sched& S, const Epi& E) {
;     ...
;             const bool last = (t == nt - 2);
;             const char* a1 = cA + (size_t)(t + 1) * kstep;
;             const char* a2 = last ? nA : cA + (size_t)(t + 2) * kstep; const char* b2 = last ? nB : cB + (size_t)(t + 2) * kstep;
;             const char* a3 = a2 + kstep; const char* b3 = b2 + kstep;
;             if (last && has_next) S.a_ready(nxt);
;             if constexpr (SP2) {
;             PG8_LDB(B0, 0, 0); PG8_LDB(B1, 0, 1); PG8_SCHED; PG8_LDA(At, 0, 0); PG8_STAGE(PG8_SA(1, 1), a1 + hstep, voffA);
;             PG8_WAIT_V(8); PG8_WAIT_L(0); PG8_BAR; PG8_MMA(0, 0, At, B0); PG8_MMA(0, 1, At, B1); PG8_BAR; PG8_SCHED;
;             PG8_LDA(At, 0, 1); PG8_STAGE(PG8_SB(0, 0), b2, voffB); PG8_STAGE(PG8_SB(0, 1), b2 + hstep, voffB); PG8_STAGE(PG8_SA(0, 0), a2, voffA);
;             PG8_WAIT_V(8); PG8_WAIT_L(0); PG8_BAR; PG8_MMA(1, 0, At, B0); PG8_MMA(1, 1, At, B1); PG8_BAR; PG8_SCHED;
;             PG8_LDB(B0, 1, 0); PG8_LDB(B1, 1, 1); PG8_SCHED; PG8_LDA(At, 1, 0); PG8_STAGE(PG8_SA(0, 1), a2 + hstep, voffA);
.LBB0_329:
	s_ashr_i32 s21, s20, 31
	s_lshl_b64 s[22:23], s[20:21], 19
	s_add_u32 s22, s94, s22
	s_addc_u32 s23, s95, s23
	s_and_b64 s[24:25], s[4:5], exec
	s_cselect_b32 s21, s23, s29
	s_cselect_b32 s27, s22, s28
	s_ashr_i32 s19, s18, 31
	s_lshl_b64 s[24:25], s[18:19], 19
	v_readlane_b32 s34, v251, 0
	v_readlane_b32 s35, v251, 1
	s_add_u32 s24, s34, s24
	s_addc_u32 s25, s35, s25
	s_and_b64 s[34:35], s[4:5], exec
	s_cselect_b32 s19, s25, s31
	s_cselect_b32 s60, s24, s30
	s_add_u32 s28, s28, 0x40080
	s_addc_u32 s29, s29, 0
	s_add_u32 s61, s30, 0x100
	s_waitcnt vmcnt(0)
	s_addc_u32 s62, s31, 0
	s_mov_b32 s63, -2
	s_add_u32 s30, s28, 0xfffc0080
	s_addc_u32 s31, s29, -1
	s_add_i32 s64, 0, 0x10000
	s_cmp_eq_u32 s63, 12
	s_cselect_b32 s35, s21, s31
	s_cselect_b32 s34, s27, s30
	v_add_u32_e32 v156, s64, v149
	s_cselect_b32 s31, s19, s62
	s_cselect_b32 s30, s60, s61
	s_add_i32 s66, 0, 0x14000
	ds_read_b128 v[144:147], v156
	ds_read_b128 v[152:155], v156 offset:1024
	ds_read_b128 v[172:175], v156 offset:2048
	ds_read_b128 v[176:179], v156 offset:3072
	v_add_u32_e32 v156, s66, v149
	ds_read_b128 v[180:183], v156
	ds_read_b128 v[184:187], v156 offset:1024
	ds_read_b128 v[188:191], v156 offset:2048
	ds_read_b128 v[192:195], v156 offset:3072
	s_add_i32 m0, s46, 0xc000
	ds_read_b128 v[196:199], v151
	ds_read_b128 v[214:217], v151 offset:1024
	ds_read_b128 v[218:221], v151 offset:2048
	ds_read_b128 v[222:225], v151 offset:3072
	ds_read_b128 v[226:229], v151 offset:4096
	ds_read_b128 v[230:233], v151 offset:5120
	ds_read_b128 v[234:237], v151 offset:6144
	ds_read_b128 v[238:241], v151 offset:7168
	global_load_lds_dwordx4 v140, s[28:29]
	s_add_i32 m0, s46, 0xe000
	s_nop 0
	global_load_lds_dwordx4 v142, s[28:29]
	s_waitcnt vmcnt(8)
	s_waitcnt lgkmcnt(0)
	s_barrier
	s_setprio 1
	s_waitcnt lgkmcnt(0)
	v_mfma_f32_16x16x32_bf16 v[62:65], v[144:147], v[196:199], 0
	v_mfma_f32_16x16x32_bf16 v[58:61], v[172:175], v[196:199], 0
	v_mfma_f32_16x16x32_bf16 v[54:57], v[144:147], v[218:221], 0
	v_mfma_f32_16x16x32_bf16 v[50:53], v[172:175], v[218:221], 0
	v_mfma_f32_16x16x32_bf16 v[46:49], v[144:147], v[226:229], 0
	v_mfma_f32_16x16x32_bf16 v[42:45], v[172:175], v[226:229], 0
	v_mfma_f32_16x16x32_bf16 v[38:41], v[144:147], v[234:237], 0
	v_mfma_f32_16x16x32_bf16 v[34:37], v[172:175], v[234:237], 0
	v_mfma_f32_16x16x32_bf16 v[62:65], v[152:155], v[214:217], v[62:65]
	v_mfma_f32_16x16x32_bf16 v[58:61], v[176:179], v[214:217], v[58:61]
	v_mfma_f32_16x16x32_bf16 v[54:57], v[152:155], v[222:225], v[54:57]
	v_mfma_f32_16x16x32_bf16 v[50:53], v[176:179], v[222:225], v[50:53]
	v_mfma_f32_16x16x32_bf16 v[46:49], v[152:155], v[230:233], v[46:49]
	v_mfma_f32_16x16x32_bf16 v[42:45], v[176:179], v[230:233], v[42:45]
	v_mfma_f32_16x16x32_bf16 v[38:41], v[152:155], v[238:241], v[38:41]
	v_mfma_f32_16x16x32_bf16 v[34:37], v[176:179], v[238:241], v[34:37]
	s_setprio 0
	s_setprio 1
	v_mfma_f32_16x16x32_bf16 v[126:129], v[180:183], v[196:199], 0
	v_mfma_f32_16x16x32_bf16 v[122:125], v[188:191], v[196:199], 0
	v_mfma_f32_16x16x32_bf16 v[118:121], v[180:183], v[218:221], 0
	v_mfma_f32_16x16x32_bf16 v[114:117], v[188:191], v[218:221], 0
	v_mfma_f32_16x16x32_bf16 v[110:113], v[180:183], v[226:229], 0
	v_mfma_f32_16x16x32_bf16 v[106:109], v[188:191], v[226:229], 0
	v_mfma_f32_16x16x32_bf16 v[102:105], v[180:183], v[234:237], 0
	v_mfma_f32_16x16x32_bf16 v[98:101], v[188:191], v[234:237], 0
	v_mfma_f32_16x16x32_bf16 v[126:129], v[184:187], v[214:217], v[126:129]
	v_mfma_f32_16x16x32_bf16 v[122:125], v[192:195], v[214:217], v[122:125]
	v_mfma_f32_16x16x32_bf16 v[118:121], v[184:187], v[222:225], v[118:121]
	v_mfma_f32_16x16x32_bf16 v[114:117], v[192:195], v[222:225], v[114:117]
	v_mfma_f32_16x16x32_bf16 v[110:113], v[184:187], v[230:233], v[110:113]
	v_mfma_f32_16x16x32_bf16 v[106:109], v[192:195], v[230:233], v[106:109]
	v_mfma_f32_16x16x32_bf16 v[102:105], v[184:187], v[238:241], v[102:105]
	v_mfma_f32_16x16x32_bf16 v[98:101], v[192:195], v[238:241], v[98:101]
	s_setprio 0
	s_barrier
	s_add_i32 s64, s64, s2
	s_mov_b32 m0, s64
	ds_read_b128 v[196:199], v151 offset:16384
	ds_read_b128 v[214:217], v151 offset:17408
	ds_read_b128 v[218:221], v151 offset:18432
	ds_read_b128 v[222:225], v151 offset:19456
	ds_read_b128 v[226:229], v151 offset:20480
	ds_read_b128 v[230:233], v151 offset:21504
	ds_read_b128 v[234:237], v151 offset:22528
	ds_read_b128 v[238:241], v151 offset:23552
	global_load_lds_dwordx4 v0, s[30:31]
	s_add_i32 m0, s64, 0x2000
	s_add_u32 s64, s30, 0x40000
	s_addc_u32 s65, s31, 0
	s_add_i32 s66, s66, s2
	global_load_lds_dwordx4 v130, s[30:31]
	s_mov_b32 m0, s66
	s_nop 0
	global_load_lds_dwordx4 v0, s[64:65]
	s_add_i32 m0, s66, 0x2000
	s_nop 0
	global_load_lds_dwordx4 v130, s[64:65]
	s_mov_b32 m0, s46
	s_nop 0
	global_load_lds_dwordx4 v134, s[34:35]
	s_mov_b32 m0, s47
	s_nop 0
	global_load_lds_dwordx4 v132, s[34:35]
	s_waitcnt vmcnt(8)
	s_waitcnt lgkmcnt(0)
	s_barrier
; #define PG8_STAGE(bufoff, gbase, voff) do { _Pragma("unroll") for (int _i = 0; _i < 2; ++_i) \
;         __builtin_amdgcn_global_load_lds((const unsigned*)((const char*)(gbase) + (voff)[_i]), (PG8_LAS unsigned*)(lds + (bufoff) + ldsw + _i * 8192), 16, 0, 0); } while (0)
; #define PG8_LDA(dst, b, h) do { _Pragma("unroll") for (int m = 0; m < 4; ++m) _Pragma("unroll") for (int k = 0; k < 2; ++k) dst[m][k] = *(const PG8_LAS bf16x8*)(lds + PG8_SA(b, h) + aoff + m * 2048 + k * 1024); } while (0)
; #define PG8_LDB(dst, b, h) do { _Pragma("unroll") for (int n = 0; n < 2; ++n) _Pragma("unroll") for (int k = 0; k < 2; ++k) dst[n][k] = *(const PG8_LAS bf16x8*)(lds + PG8_SB(b, h) + boff + n * 2048 + k * 1024); } while (0)
; #define PG8_MMA(ai, bj, At, Bt) do { __builtin_amdgcn_s_setprio(1); _Pragma("unroll") for (int m = 0; m < 4; ++m) _Pragma("unroll") for (int n = 0; n < 2; ++n) _Pragma("unroll") for (int k = 0; k < 2; ++k) \
;         acc[ai][bj][m][n] = __builtin_amdgcn_mfma_f32_16x16x32_bf16(Bt[n][k], At[m][k], acc[ai][bj][m][n], 0, 0, 0); __builtin_amdgcn_s_setprio(0); } while (0)
; #define PG8_WAIT_V(n) asm volatile("s_waitcnt vmcnt(" #n ")" ::: "memory")
; #define PG8_WAIT_L(n) asm volatile("s_waitcnt lgkmcnt(" #n ")" ::: "memory")
; #define PG8_BAR __builtin_amdgcn_s_barrier()
; #define PG8_SCHED __builtin_amdgcn_sched_barrier(0)
; template <class Epi, class Sched, bool ALIGN_EPI = false, bool SP2 = false>
; __device__ __forceinline__ void gemm_phase(PG8_LAS unsigned char* lds, const Gemm g, const Sched& S, const Epi& E) {
;     ...
;             PG8_LDA(At, 0, 1); PG8_STAGE(PG8_SB(0, 0), b2, voffB); PG8_STAGE(PG8_SB(0, 1), b2 + hstep, voffB); PG8_STAGE(PG8_SA(0, 0), a2, voffA);
;             PG8_WAIT_V(8); PG8_WAIT_L(0); PG8_BAR; PG8_MMA(1, 0, At, B0); PG8_MMA(1, 1, At, B1); PG8_BAR; PG8_SCHED;
;             PG8_LDB(B0, 1, 0); PG8_LDB(B1, 1, 1); PG8_SCHED; PG8_LDA(At, 1, 0); PG8_STAGE(PG8_SA(0, 1), a2 + hstep, voffA);
;             PG8_WAIT_V(8); PG8_WAIT_L(0); PG8_BAR; PG8_MMA(0, 0, At, B0); PG8_MMA(0, 1, At, B1); PG8_BAR; PG8_SCHED;
;             PG8_LDA(At, 1, 1); PG8_STAGE(PG8_SB(1, 0), b3, voffB); PG8_STAGE(PG8_SB(1, 1), b3 + hstep, voffB); PG8_STAGE(PG8_SA(1, 0), a3, voffA);
	s_setprio 1
	s_waitcnt lgkmcnt(0)
	v_mfma_f32_16x16x32_bf16 v[30:33], v[144:147], v[196:199], 0
	v_mfma_f32_16x16x32_bf16 v[26:29], v[172:175], v[196:199], 0
	v_mfma_f32_16x16x32_bf16 v[22:25], v[144:147], v[218:221], 0
	v_mfma_f32_16x16x32_bf16 v[18:21], v[172:175], v[218:221], 0
	v_mfma_f32_16x16x32_bf16 v[14:17], v[144:147], v[226:229], 0
	v_mfma_f32_16x16x32_bf16 v[10:13], v[172:175], v[226:229], 0
	v_mfma_f32_16x16x32_bf16 v[6:9], v[144:147], v[234:237], 0
	v_mfma_f32_16x16x32_bf16 v[2:5], v[172:175], v[234:237], 0
	v_mfma_f32_16x16x32_bf16 v[30:33], v[152:155], v[214:217], v[30:33]
	v_mfma_f32_16x16x32_bf16 v[26:29], v[176:179], v[214:217], v[26:29]
	v_mfma_f32_16x16x32_bf16 v[22:25], v[152:155], v[222:225], v[22:25]
	v_mfma_f32_16x16x32_bf16 v[18:21], v[176:179], v[222:225], v[18:21]
	v_mfma_f32_16x16x32_bf16 v[14:17], v[152:155], v[230:233], v[14:17]
	v_mfma_f32_16x16x32_bf16 v[10:13], v[176:179], v[230:233], v[10:13]
	v_mfma_f32_16x16x32_bf16 v[6:9], v[152:155], v[238:241], v[6:9]
	v_mfma_f32_16x16x32_bf16 v[2:5], v[176:179], v[238:241], v[2:5]
	s_setprio 0
	s_setprio 1
	v_mfma_f32_16x16x32_bf16 v[94:97], v[180:183], v[196:199], 0
	v_mfma_f32_16x16x32_bf16 v[90:93], v[188:191], v[196:199], 0
	v_mfma_f32_16x16x32_bf16 v[86:89], v[180:183], v[218:221], 0
	v_mfma_f32_16x16x32_bf16 v[82:85], v[188:191], v[218:221], 0
	v_mfma_f32_16x16x32_bf16 v[78:81], v[180:183], v[226:229], 0
	v_mfma_f32_16x16x32_bf16 v[74:77], v[188:191], v[226:229], 0
	v_mfma_f32_16x16x32_bf16 v[70:73], v[180:183], v[234:237], 0
	v_mfma_f32_16x16x32_bf16 v[66:69], v[188:191], v[234:237], 0
	v_mfma_f32_16x16x32_bf16 v[94:97], v[184:187], v[214:217], v[94:97]
	v_mfma_f32_16x16x32_bf16 v[90:93], v[192:195], v[214:217], v[90:93]
	v_mfma_f32_16x16x32_bf16 v[86:89], v[184:187], v[222:225], v[86:89]
	v_mfma_f32_16x16x32_bf16 v[82:85], v[192:195], v[222:225], v[82:85]
	v_mfma_f32_16x16x32_bf16 v[78:81], v[184:187], v[230:233], v[78:81]
	v_mfma_f32_16x16x32_bf16 v[74:77], v[192:195], v[230:233], v[74:77]
	v_mfma_f32_16x16x32_bf16 v[70:73], v[184:187], v[238:241], v[70:73]
	v_mfma_f32_16x16x32_bf16 v[66:69], v[192:195], v[238:241], v[66:69]
	s_setprio 0
	s_barrier
	s_add_i32 s64, 0, 0x18000
	v_add_u32_e32 v158, s64, v149
	s_add_i32 s65, 0, 0x1c000
	ds_read_b128 v[144:147], v158
	ds_read_b128 v[152:155], v158 offset:1024
	ds_read_b128 v[172:175], v158 offset:2048
	ds_read_b128 v[176:179], v158 offset:3072
	v_add_u32_e32 v158, s65, v149
	ds_read_b128 v[180:183], v158
	ds_read_b128 v[184:187], v158 offset:1024
	ds_read_b128 v[188:191], v158 offset:2048
	ds_read_b128 v[192:195], v158 offset:3072
	s_add_u32 s34, s34, 0x40000
	s_addc_u32 s35, s35, 0
	s_mov_b32 m0, s48
	ds_read_b128 v[196:199], v151 offset:32768
	ds_read_b128 v[214:217], v151 offset:33792
	ds_read_b128 v[218:221], v151 offset:34816
	ds_read_b128 v[222:225], v151 offset:35840
	ds_read_b128 v[226:229], v151 offset:36864
	ds_read_b128 v[230:233], v151 offset:37888
	ds_read_b128 v[234:237], v151 offset:38912
	ds_read_b128 v[238:241], v151 offset:39936
	global_load_lds_dwordx4 v134, s[34:35]
	s_mov_b32 m0, s49
	s_nop 0
	global_load_lds_dwordx4 v132, s[34:35]
	s_waitcnt vmcnt(8)
	s_waitcnt lgkmcnt(0)
	s_barrier
	s_setprio 1
	s_waitcnt lgkmcnt(0)
	v_mfma_f32_16x16x32_bf16 v[62:65], v[144:147], v[196:199], v[62:65]
	v_mfma_f32_16x16x32_bf16 v[58:61], v[172:175], v[196:199], v[58:61]
	v_mfma_f32_16x16x32_bf16 v[54:57], v[144:147], v[218:221], v[54:57]
	v_mfma_f32_16x16x32_bf16 v[50:53], v[172:175], v[218:221], v[50:53]
	v_mfma_f32_16x16x32_bf16 v[46:49], v[144:147], v[226:229], v[46:49]
	v_mfma_f32_16x16x32_bf16 v[42:45], v[172:175], v[226:229], v[42:45]
	v_mfma_f32_16x16x32_bf16 v[38:41], v[144:147], v[234:237], v[38:41]
	v_mfma_f32_16x16x32_bf16 v[34:37], v[172:175], v[234:237], v[34:37]
	v_mfma_f32_16x16x32_bf16 v[62:65], v[152:155], v[214:217], v[62:65]
	v_mfma_f32_16x16x32_bf16 v[58:61], v[176:179], v[214:217], v[58:61]
	v_mfma_f32_16x16x32_bf16 v[54:57], v[152:155], v[222:225], v[54:57]
	v_mfma_f32_16x16x32_bf16 v[50:53], v[176:179], v[222:225], v[50:53]
	v_mfma_f32_16x16x32_bf16 v[46:49], v[152:155], v[230:233], v[46:49]
	v_mfma_f32_16x16x32_bf16 v[42:45], v[176:179], v[230:233], v[42:45]
	v_mfma_f32_16x16x32_bf16 v[38:41], v[152:155], v[238:241], v[38:41]
	v_mfma_f32_16x16x32_bf16 v[34:37], v[176:179], v[238:241], v[34:37]
	s_setprio 0
	s_setprio 1
	v_mfma_f32_16x16x32_bf16 v[126:129], v[180:183], v[196:199], v[126:129]
	v_mfma_f32_16x16x32_bf16 v[122:125], v[188:191], v[196:199], v[122:125]
	v_mfma_f32_16x16x32_bf16 v[118:121], v[180:183], v[218:221], v[118:121]
	v_mfma_f32_16x16x32_bf16 v[114:117], v[188:191], v[218:221], v[114:117]
	v_mfma_f32_16x16x32_bf16 v[110:113], v[180:183], v[226:229], v[110:113]
	v_mfma_f32_16x16x32_bf16 v[106:109], v[188:191], v[226:229], v[106:109]
	v_mfma_f32_16x16x32_bf16 v[102:105], v[180:183], v[234:237], v[102:105]
	v_mfma_f32_16x16x32_bf16 v[98:101], v[188:191], v[234:237], v[98:101]
	v_mfma_f32_16x16x32_bf16 v[126:129], v[184:187], v[214:217], v[126:129]
	v_mfma_f32_16x16x32_bf16 v[122:125], v[192:195], v[214:217], v[122:125]
	v_mfma_f32_16x16x32_bf16 v[118:121], v[184:187], v[222:225], v[118:121]
	v_mfma_f32_16x16x32_bf16 v[114:117], v[192:195], v[222:225], v[114:117]
	v_mfma_f32_16x16x32_bf16 v[110:113], v[184:187], v[230:233], v[110:113]
	v_mfma_f32_16x16x32_bf16 v[106:109], v[192:195], v[230:233], v[106:109]
	v_mfma_f32_16x16x32_bf16 v[102:105], v[184:187], v[238:241], v[102:105]
	v_mfma_f32_16x16x32_bf16 v[98:101], v[192:195], v[238:241], v[98:101]
	s_setprio 0
	s_barrier
; #define PG8_STAGE(bufoff, gbase, voff) do { _Pragma("unroll") for (int _i = 0; _i < 2; ++_i) \
;         __builtin_amdgcn_global_load_lds((const unsigned*)((const char*)(gbase) + (voff)[_i]), (PG8_LAS unsigned*)(lds + (bufoff) + ldsw + _i * 8192), 16, 0, 0); } while (0)
; #define PG8_LDA(dst, b, h) do { _Pragma("unroll") for (int m = 0; m < 4; ++m) _Pragma("unroll") for (int k = 0; k < 2; ++k) dst[m][k] = *(const PG8_LAS bf16x8*)(lds + PG8_SA(b, h) + aoff + m * 2048 + k * 1024); } while (0)
; #define PG8_LDB(dst, b, h) do { _Pragma("unroll") for (int n = 0; n < 2; ++n) _Pragma("unroll") for (int k = 0; k < 2; ++k) dst[n][k] = *(const PG8_LAS bf16x8*)(lds + PG8_SB(b, h) + boff + n * 2048 + k * 1024); } while (0)
; #define PG8_MMA(ai, bj, At, Bt) do { __builtin_amdgcn_s_setprio(1); _Pragma("unroll") for (int m = 0; m < 4; ++m) _Pragma("unroll") for (int n = 0; n < 2; ++n) _Pragma("unroll") for (int k = 0; k < 2; ++k) \
;         acc[ai][bj][m][n] = __builtin_amdgcn_mfma_f32_16x16x32_bf16(Bt[n][k], At[m][k], acc[ai][bj][m][n], 0, 0, 0); __builtin_amdgcn_s_setprio(0); } while (0)
; #define PG8_WAIT_V(n) asm volatile("s_waitcnt vmcnt(" #n ")" ::: "memory")
; #define PG8_WAIT_L(n) asm volatile("s_waitcnt lgkmcnt(" #n ")" ::: "memory")
; template <class Epi, class Sched, bool ALIGN_EPI = false, bool SP2 = false>
; __device__ __forceinline__ void gemm_phase(PG8_LAS unsigned char* lds, const Gemm g, const Sched& S, const Epi& E) {
;     ...
;         for (int t = 0; t < nt; t += 2) {
;             const bool last = (t == nt - 2);
;             const char* a1 = cA + (size_t)(t + 1) * kstep;
;             const char* a2 = last ? nA : cA + (size_t)(t + 2) * kstep; const char* b2 = last ? nB : cB + (size_t)(t + 2) * kstep;
;             const char* a3 = a2 + kstep; const char* b3 = b2 + kstep;
;             if (last && has_next) S.a_ready(nxt);
;     ...
;             PG8_LDB(B0, 1, 0); PG8_LDB(B1, 1, 1); PG8_SCHED; PG8_LDA(At, 1, 0); PG8_STAGE(PG8_SA(0, 1), a2 + hstep, voffA);
;             PG8_WAIT_V(8); PG8_WAIT_L(0); PG8_BAR; PG8_MMA(0, 0, At, B0); PG8_MMA(0, 1, At, B1); PG8_BAR; PG8_SCHED;
;             PG8_LDA(At, 1, 1); PG8_STAGE(PG8_SB(1, 0), b3, voffB); PG8_STAGE(PG8_SB(1, 1), b3 + hstep, voffB); PG8_STAGE(PG8_SA(1, 0), a3, voffA);
;             PG8_WAIT_V(8); PG8_WAIT_L(0); PG8_BAR; PG8_MMA(1, 0, At, B0); PG8_MMA(1, 1, At, B1); PG8_BAR; PG8_SCHED;
	s_add_u32 s98, s34, 0xfffc0080
	s_addc_u32 s99, s35, -1
	s_add_i32 s34, s64, s2
	s_add_u32 s100, s30, 0x80
	s_addc_u32 s101, s31, 0
	s_mov_b32 m0, s34
	ds_read_b128 v[196:199], v151 offset:49152
	ds_read_b128 v[214:217], v151 offset:50176
	ds_read_b128 v[218:221], v151 offset:51200
	ds_read_b128 v[222:225], v151 offset:52224
	ds_read_b128 v[226:229], v151 offset:53248
	ds_read_b128 v[230:233], v151 offset:54272
	ds_read_b128 v[234:237], v151 offset:55296
	ds_read_b128 v[238:241], v151 offset:56320
	global_load_lds_dwordx4 v0, s[100:101]
	s_add_i32 m0, s34, 0x2000
	s_add_u32 s30, s30, 0x40080
	s_addc_u32 s31, s31, 0
	s_add_i32 s34, s65, s2
	global_load_lds_dwordx4 v130, s[100:101]
	s_mov_b32 m0, s34
	s_nop 0
	global_load_lds_dwordx4 v0, s[30:31]
	s_add_i32 m0, s34, 0x2000
	s_nop 0
	global_load_lds_dwordx4 v130, s[30:31]
	s_mov_b32 m0, s52
	s_nop 0
	global_load_lds_dwordx4 v134, s[98:99]
	s_mov_b32 m0, s53
	s_nop 0
	global_load_lds_dwordx4 v132, s[98:99]
	s_waitcnt vmcnt(8)
	s_waitcnt lgkmcnt(0)
	s_barrier
	s_setprio 1
	s_waitcnt lgkmcnt(0)
	v_mfma_f32_16x16x32_bf16 v[30:33], v[144:147], v[196:199], v[30:33]
	v_mfma_f32_16x16x32_bf16 v[26:29], v[172:175], v[196:199], v[26:29]
	v_mfma_f32_16x16x32_bf16 v[22:25], v[144:147], v[218:221], v[22:25]
	v_mfma_f32_16x16x32_bf16 v[18:21], v[172:175], v[218:221], v[18:21]
	v_mfma_f32_16x16x32_bf16 v[14:17], v[144:147], v[226:229], v[14:17]
	v_mfma_f32_16x16x32_bf16 v[10:13], v[172:175], v[226:229], v[10:13]
	v_mfma_f32_16x16x32_bf16 v[6:9], v[144:147], v[234:237], v[6:9]
	v_mfma_f32_16x16x32_bf16 v[2:5], v[172:175], v[234:237], v[2:5]
	v_mfma_f32_16x16x32_bf16 v[30:33], v[152:155], v[214:217], v[30:33]
	v_mfma_f32_16x16x32_bf16 v[26:29], v[176:179], v[214:217], v[26:29]
	v_mfma_f32_16x16x32_bf16 v[22:25], v[152:155], v[222:225], v[22:25]
	v_mfma_f32_16x16x32_bf16 v[18:21], v[176:179], v[222:225], v[18:21]
	v_mfma_f32_16x16x32_bf16 v[14:17], v[152:155], v[230:233], v[14:17]
	v_mfma_f32_16x16x32_bf16 v[10:13], v[176:179], v[230:233], v[10:13]
	v_mfma_f32_16x16x32_bf16 v[6:9], v[152:155], v[238:241], v[6:9]
	v_mfma_f32_16x16x32_bf16 v[2:5], v[176:179], v[238:241], v[2:5]
	s_setprio 0
	s_setprio 1
	v_mfma_f32_16x16x32_bf16 v[94:97], v[180:183], v[196:199], v[94:97]
	v_mfma_f32_16x16x32_bf16 v[90:93], v[188:191], v[196:199], v[90:93]
	v_mfma_f32_16x16x32_bf16 v[86:89], v[180:183], v[218:221], v[86:89]
	v_mfma_f32_16x16x32_bf16 v[82:85], v[188:191], v[218:221], v[82:85]
	v_mfma_f32_16x16x32_bf16 v[78:81], v[180:183], v[226:229], v[78:81]
	v_mfma_f32_16x16x32_bf16 v[74:77], v[188:191], v[226:229], v[74:77]
	v_mfma_f32_16x16x32_bf16 v[70:73], v[180:183], v[234:237], v[70:73]
	v_mfma_f32_16x16x32_bf16 v[66:69], v[188:191], v[234:237], v[66:69]
	v_mfma_f32_16x16x32_bf16 v[94:97], v[184:187], v[214:217], v[94:97]
	v_mfma_f32_16x16x32_bf16 v[90:93], v[192:195], v[214:217], v[90:93]
	v_mfma_f32_16x16x32_bf16 v[86:89], v[184:187], v[222:225], v[86:89]
	v_mfma_f32_16x16x32_bf16 v[82:85], v[192:195], v[222:225], v[82:85]
	v_mfma_f32_16x16x32_bf16 v[78:81], v[184:187], v[230:233], v[78:81]
	v_mfma_f32_16x16x32_bf16 v[74:77], v[192:195], v[230:233], v[74:77]
	v_mfma_f32_16x16x32_bf16 v[70:73], v[184:187], v[238:241], v[70:73]
	v_mfma_f32_16x16x32_bf16 v[66:69], v[192:195], v[238:241], v[66:69]
	s_setprio 0
	s_barrier
	s_add_i32 s63, s63, 2
	s_add_u32 s28, s28, 0x100
	s_addc_u32 s29, s29, 0
	s_add_u32 s61, s61, 0x100
	s_addc_u32 s62, s62, 0
.LBB0_330:
	s_add_u32 s30, s28, 0xfffc0080
	s_addc_u32 s31, s29, -1
	s_add_i32 s64, 0, 0x10000
	s_cmp_eq_u32 s63, 12
	s_cselect_b32 s35, s21, s31
	s_cselect_b32 s34, s27, s30
	v_add_u32_e32 v156, s64, v149
	s_cselect_b32 s31, s19, s62
	s_cselect_b32 s30, s60, s61
	s_add_i32 s66, 0, 0x14000
	ds_read_b128 v[144:147], v156
	ds_read_b128 v[152:155], v156 offset:1024
	ds_read_b128 v[172:175], v156 offset:2048
	ds_read_b128 v[176:179], v156 offset:3072
	v_add_u32_e32 v156, s66, v149
	ds_read_b128 v[180:183], v156
	ds_read_b128 v[184:187], v156 offset:1024
	ds_read_b128 v[188:191], v156 offset:2048
	ds_read_b128 v[192:195], v156 offset:3072
	s_add_i32 m0, s46, 0xc000
	ds_read_b128 v[196:199], v151
	ds_read_b128 v[214:217], v151 offset:1024
	ds_read_b128 v[218:221], v151 offset:2048
	ds_read_b128 v[222:225], v151 offset:3072
	ds_read_b128 v[226:229], v151 offset:4096
	ds_read_b128 v[230:233], v151 offset:5120
	ds_read_b128 v[234:237], v151 offset:6144
	ds_read_b128 v[238:241], v151 offset:7168
	global_load_lds_dwordx4 v140, s[28:29]
	s_add_i32 m0, s46, 0xe000
	s_nop 0
	global_load_lds_dwordx4 v142, s[28:29]
	s_waitcnt vmcnt(8)
	s_waitcnt lgkmcnt(0)
	s_barrier
; #define PG8_STAGE(bufoff, gbase, voff) do { _Pragma("unroll") for (int _i = 0; _i < 2; ++_i) \
;         __builtin_amdgcn_global_load_lds((const unsigned*)((const char*)(gbase) + (voff)[_i]), (PG8_LAS unsigned*)(lds + (bufoff) + ldsw + _i * 8192), 16, 0, 0); } while (0)
; #define PG8_LDA(dst, b, h) do { _Pragma("unroll") for (int m = 0; m < 4; ++m) _Pragma("unroll") for (int k = 0; k < 2; ++k) dst[m][k] = *(const PG8_LAS bf16x8*)(lds + PG8_SA(b, h) + aoff + m * 2048 + k * 1024); } while (0)
; #define PG8_LDB(dst, b, h) do { _Pragma("unroll") for (int n = 0; n < 2; ++n) _Pragma("unroll") for (int k = 0; k < 2; ++k) dst[n][k] = *(const PG8_LAS bf16x8*)(lds + PG8_SB(b, h) + boff + n * 2048 + k * 1024); } while (0)
; #define PG8_MMA(ai, bj, At, Bt) do { __builtin_amdgcn_s_setprio(1); _Pragma("unroll") for (int m = 0; m < 4; ++m) _Pragma("unroll") for (int n = 0; n < 2; ++n) _Pragma("unroll") for (int k = 0; k < 2; ++k) \
;         acc[ai][bj][m][n] = __builtin_amdgcn_mfma_f32_16x16x32_bf16(Bt[n][k], At[m][k], acc[ai][bj][m][n], 0, 0, 0); __builtin_amdgcn_s_setprio(0); } while (0)
; #define PG8_WAIT_V(n) asm volatile("s_waitcnt vmcnt(" #n ")" ::: "memory")
; #define PG8_WAIT_L(n) asm volatile("s_waitcnt lgkmcnt(" #n ")" ::: "memory")
; #define PG8_BAR __builtin_amdgcn_s_barrier()
; #define PG8_SCHED __builtin_amdgcn_sched_barrier(0)
; template <class Epi, class Sched, bool ALIGN_EPI = false, bool SP2 = false>
; __device__ __forceinline__ void gemm_phase(PG8_LAS unsigned char* lds, const Gemm g, const Sched& S, const Epi& E) {
;     ...
;             PG8_LDB(B0, 0, 0); PG8_LDB(B1, 0, 1); PG8_SCHED; PG8_LDA(At, 0, 0); PG8_STAGE(PG8_SA(1, 1), a1 + hstep, voffA);
;             PG8_WAIT_V(8); PG8_WAIT_L(0); PG8_BAR; PG8_MMA(0, 0, At, B0); PG8_MMA(0, 1, At, B1); PG8_BAR; PG8_SCHED;
;             PG8_LDA(At, 0, 1); PG8_STAGE(PG8_SB(0, 0), b2, voffB); PG8_STAGE(PG8_SB(0, 1), b2 + hstep, voffB); PG8_STAGE(PG8_SA(0, 0), a2, voffA);
;             PG8_WAIT_V(8); PG8_WAIT_L(0); PG8_BAR; PG8_MMA(1, 0, At, B0); PG8_MMA(1, 1, At, B1); PG8_BAR; PG8_SCHED;
;             PG8_LDB(B0, 1, 0); PG8_LDB(B1, 1, 1); PG8_SCHED; PG8_LDA(At, 1, 0); PG8_STAGE(PG8_SA(0, 1), a2 + hstep, voffA);
	s_setprio 1
	s_waitcnt lgkmcnt(0)
	v_mfma_f32_16x16x32_bf16 v[62:65], v[144:147], v[196:199], v[62:65]
	v_mfma_f32_16x16x32_bf16 v[58:61], v[172:175], v[196:199], v[58:61]
	v_mfma_f32_16x16x32_bf16 v[54:57], v[144:147], v[218:221], v[54:57]
	v_mfma_f32_16x16x32_bf16 v[50:53], v[172:175], v[218:221], v[50:53]
	v_mfma_f32_16x16x32_bf16 v[46:49], v[144:147], v[226:229], v[46:49]
	v_mfma_f32_16x16x32_bf16 v[42:45], v[172:175], v[226:229], v[42:45]
	v_mfma_f32_16x16x32_bf16 v[38:41], v[144:147], v[234:237], v[38:41]
	v_mfma_f32_16x16x32_bf16 v[34:37], v[172:175], v[234:237], v[34:37]
	v_mfma_f32_16x16x32_bf16 v[62:65], v[152:155], v[214:217], v[62:65]
	v_mfma_f32_16x16x32_bf16 v[58:61], v[176:179], v[214:217], v[58:61]
	v_mfma_f32_16x16x32_bf16 v[54:57], v[152:155], v[222:225], v[54:57]
	v_mfma_f32_16x16x32_bf16 v[50:53], v[176:179], v[222:225], v[50:53]
	v_mfma_f32_16x16x32_bf16 v[46:49], v[152:155], v[230:233], v[46:49]
	v_mfma_f32_16x16x32_bf16 v[42:45], v[176:179], v[230:233], v[42:45]
	v_mfma_f32_16x16x32_bf16 v[38:41], v[152:155], v[238:241], v[38:41]
	v_mfma_f32_16x16x32_bf16 v[34:37], v[176:179], v[238:241], v[34:37]
	s_setprio 0
	s_setprio 1
	v_mfma_f32_16x16x32_bf16 v[126:129], v[180:183], v[196:199], v[126:129]
	v_mfma_f32_16x16x32_bf16 v[122:125], v[188:191], v[196:199], v[122:125]
	v_mfma_f32_16x16x32_bf16 v[118:121], v[180:183], v[218:221], v[118:121]
	v_mfma_f32_16x16x32_bf16 v[114:117], v[188:191], v[218:221], v[114:117]
	v_mfma_f32_16x16x32_bf16 v[110:113], v[180:183], v[226:229], v[110:113]
	v_mfma_f32_16x16x32_bf16 v[106:109], v[188:191], v[226:229], v[106:109]
	v_mfma_f32_16x16x32_bf16 v[102:105], v[180:183], v[234:237], v[102:105]
	v_mfma_f32_16x16x32_bf16 v[98:101], v[188:191], v[234:237], v[98:101]
	v_mfma_f32_16x16x32_bf16 v[126:129], v[184:187], v[214:217], v[126:129]
	v_mfma_f32_16x16x32_bf16 v[122:125], v[192:195], v[214:217], v[122:125]
	v_mfma_f32_16x16x32_bf16 v[118:121], v[184:187], v[222:225], v[118:121]
	v_mfma_f32_16x16x32_bf16 v[114:117], v[192:195], v[222:225], v[114:117]
	v_mfma_f32_16x16x32_bf16 v[110:113], v[184:187], v[230:233], v[110:113]
	v_mfma_f32_16x16x32_bf16 v[106:109], v[192:195], v[230:233], v[106:109]
	v_mfma_f32_16x16x32_bf16 v[102:105], v[184:187], v[238:241], v[102:105]
	v_mfma_f32_16x16x32_bf16 v[98:101], v[192:195], v[238:241], v[98:101]
	s_setprio 0
	s_barrier
	s_add_i32 s64, s64, s2
	s_mov_b32 m0, s64
	ds_read_b128 v[196:199], v151 offset:16384
	ds_read_b128 v[214:217], v151 offset:17408
	ds_read_b128 v[218:221], v151 offset:18432
	ds_read_b128 v[222:225], v151 offset:19456
	ds_read_b128 v[226:229], v151 offset:20480
	ds_read_b128 v[230:233], v151 offset:21504
	ds_read_b128 v[234:237], v151 offset:22528
	ds_read_b128 v[238:241], v151 offset:23552
	global_load_lds_dwordx4 v0, s[30:31]
	s_add_i32 m0, s64, 0x2000
	s_add_u32 s64, s30, 0x40000
	s_addc_u32 s65, s31, 0
	s_add_i32 s66, s66, s2
	global_load_lds_dwordx4 v130, s[30:31]
	s_mov_b32 m0, s66
	s_nop 0
	global_load_lds_dwordx4 v0, s[64:65]
	s_add_i32 m0, s66, 0x2000
	s_nop 0
	global_load_lds_dwordx4 v130, s[64:65]
	s_mov_b32 m0, s46
	s_nop 0
	global_load_lds_dwordx4 v134, s[34:35]
	s_mov_b32 m0, s47
	s_nop 0
	global_load_lds_dwordx4 v132, s[34:35]
	s_waitcnt vmcnt(8)
	s_waitcnt lgkmcnt(0)
	s_barrier
	s_setprio 1
	s_waitcnt lgkmcnt(0)
	v_mfma_f32_16x16x32_bf16 v[30:33], v[144:147], v[196:199], v[30:33]
	v_mfma_f32_16x16x32_bf16 v[26:29], v[172:175], v[196:199], v[26:29]
	v_mfma_f32_16x16x32_bf16 v[22:25], v[144:147], v[218:221], v[22:25]
	v_mfma_f32_16x16x32_bf16 v[18:21], v[172:175], v[218:221], v[18:21]
	v_mfma_f32_16x16x32_bf16 v[14:17], v[144:147], v[226:229], v[14:17]
	v_mfma_f32_16x16x32_bf16 v[10:13], v[172:175], v[226:229], v[10:13]
	v_mfma_f32_16x16x32_bf16 v[6:9], v[144:147], v[234:237], v[6:9]
	v_mfma_f32_16x16x32_bf16 v[2:5], v[172:175], v[234:237], v[2:5]
	v_mfma_f32_16x16x32_bf16 v[30:33], v[152:155], v[214:217], v[30:33]
	v_mfma_f32_16x16x32_bf16 v[26:29], v[176:179], v[214:217], v[26:29]
	v_mfma_f32_16x16x32_bf16 v[22:25], v[152:155], v[222:225], v[22:25]
	v_mfma_f32_16x16x32_bf16 v[18:21], v[176:179], v[222:225], v[18:21]
	v_mfma_f32_16x16x32_bf16 v[14:17], v[152:155], v[230:233], v[14:17]
	v_mfma_f32_16x16x32_bf16 v[10:13], v[176:179], v[230:233], v[10:13]
	v_mfma_f32_16x16x32_bf16 v[6:9], v[152:155], v[238:241], v[6:9]
	v_mfma_f32_16x16x32_bf16 v[2:5], v[176:179], v[238:241], v[2:5]
	s_setprio 0
	s_setprio 1
	v_mfma_f32_16x16x32_bf16 v[94:97], v[180:183], v[196:199], v[94:97]
	v_mfma_f32_16x16x32_bf16 v[90:93], v[188:191], v[196:199], v[90:93]
	v_mfma_f32_16x16x32_bf16 v[86:89], v[180:183], v[218:221], v[86:89]
	v_mfma_f32_16x16x32_bf16 v[82:85], v[188:191], v[218:221], v[82:85]
	v_mfma_f32_16x16x32_bf16 v[78:81], v[180:183], v[226:229], v[78:81]
	v_mfma_f32_16x16x32_bf16 v[74:77], v[188:191], v[226:229], v[74:77]
	v_mfma_f32_16x16x32_bf16 v[70:73], v[180:183], v[234:237], v[70:73]
	v_mfma_f32_16x16x32_bf16 v[66:69], v[188:191], v[234:237], v[66:69]
	v_mfma_f32_16x16x32_bf16 v[94:97], v[184:187], v[214:217], v[94:97]
	v_mfma_f32_16x16x32_bf16 v[90:93], v[192:195], v[214:217], v[90:93]
	v_mfma_f32_16x16x32_bf16 v[86:89], v[184:187], v[222:225], v[86:89]
	v_mfma_f32_16x16x32_bf16 v[82:85], v[192:195], v[222:225], v[82:85]
	v_mfma_f32_16x16x32_bf16 v[78:81], v[184:187], v[230:233], v[78:81]
	v_mfma_f32_16x16x32_bf16 v[74:77], v[192:195], v[230:233], v[74:77]
	v_mfma_f32_16x16x32_bf16 v[70:73], v[184:187], v[238:241], v[70:73]
	v_mfma_f32_16x16x32_bf16 v[66:69], v[192:195], v[238:241], v[66:69]
	s_setprio 0
	s_barrier
; #define PG8_STAGE(bufoff, gbase, voff) do { _Pragma("unroll") for (int _i = 0; _i < 2; ++_i) \
;         __builtin_amdgcn_global_load_lds((const unsigned*)((const char*)(gbase) + (voff)[_i]), (PG8_LAS unsigned*)(lds + (bufoff) + ldsw + _i * 8192), 16, 0, 0); } while (0)
; #define PG8_LDA(dst, b, h) do { _Pragma("unroll") for (int m = 0; m < 4; ++m) _Pragma("unroll") for (int k = 0; k < 2; ++k) dst[m][k] = *(const PG8_LAS bf16x8*)(lds + PG8_SA(b, h) + aoff + m * 2048 + k * 1024); } while (0)
; #define PG8_LDB(dst, b, h) do { _Pragma("unroll") for (int n = 0; n < 2; ++n) _Pragma("unroll") for (int k = 0; k < 2; ++k) dst[n][k] = *(const PG8_LAS bf16x8*)(lds + PG8_SB(b, h) + boff + n * 2048 + k * 1024); } while (0)
; #define PG8_MMA(ai, bj, At, Bt) do { __builtin_amdgcn_s_setprio(1); _Pragma("unroll") for (int m = 0; m < 4; ++m) _Pragma("unroll") for (int n = 0; n < 2; ++n) _Pragma("unroll") for (int k = 0; k < 2; ++k) \
;         acc[ai][bj][m][n] = __builtin_amdgcn_mfma_f32_16x16x32_bf16(Bt[n][k], At[m][k], acc[ai][bj][m][n], 0, 0, 0); __builtin_amdgcn_s_setprio(0); } while (0)
; #define PG8_WAIT_V(n) asm volatile("s_waitcnt vmcnt(" #n ")" ::: "memory")
; #define PG8_WAIT_L(n) asm volatile("s_waitcnt lgkmcnt(" #n ")" ::: "memory")
; #define PG8_BAR __builtin_amdgcn_s_barrier()
; #define PG8_SCHED __builtin_amdgcn_sched_barrier(0)
; template <class Epi, class Sched, bool ALIGN_EPI = false, bool SP2 = false>
; __device__ __forceinline__ void gemm_phase(PG8_LAS unsigned char* lds, const Gemm g, const Sched& S, const Epi& E) {
;     ...
;             PG8_LDA(At, 0, 1); PG8_STAGE(PG8_SB(0, 0), b2, voffB); PG8_STAGE(PG8_SB(0, 1), b2 + hstep, voffB); PG8_STAGE(PG8_SA(0, 0), a2, voffA);
;             PG8_WAIT_V(8); PG8_WAIT_L(0); PG8_BAR; PG8_MMA(1, 0, At, B0); PG8_MMA(1, 1, At, B1); PG8_BAR; PG8_SCHED;
;             PG8_LDB(B0, 1, 0); PG8_LDB(B1, 1, 1); PG8_SCHED; PG8_LDA(At, 1, 0); PG8_STAGE(PG8_SA(0, 1), a2 + hstep, voffA);
;             PG8_WAIT_V(8); PG8_WAIT_L(0); PG8_BAR; PG8_MMA(0, 0, At, B0); PG8_MMA(0, 1, At, B1); PG8_BAR; PG8_SCHED;
;             PG8_LDA(At, 1, 1); PG8_STAGE(PG8_SB(1, 0), b3, voffB); PG8_STAGE(PG8_SB(1, 1), b3 + hstep, voffB); PG8_STAGE(PG8_SA(1, 0), a3, voffA);
;             PG8_WAIT_V(8); PG8_WAIT_L(0); PG8_BAR; PG8_MMA(1, 0, At, B0); PG8_MMA(1, 1, At, B1); PG8_BAR; PG8_SCHED;
	s_add_i32 s64, 0, 0x18000
	v_add_u32_e32 v158, s64, v149
	s_add_i32 s65, 0, 0x1c000
	ds_read_b128 v[144:147], v158
	ds_read_b128 v[152:155], v158 offset:1024
	ds_read_b128 v[172:175], v158 offset:2048
	ds_read_b128 v[176:179], v158 offset:3072
	v_add_u32_e32 v158, s65, v149
	ds_read_b128 v[180:183], v158
	ds_read_b128 v[184:187], v158 offset:1024
	ds_read_b128 v[188:191], v158 offset:2048
	ds_read_b128 v[192:195], v158 offset:3072
	s_add_u32 s34, s34, 0x40000
	s_addc_u32 s35, s35, 0
	s_mov_b32 m0, s48
	ds_read_b128 v[196:199], v151 offset:32768
	ds_read_b128 v[214:217], v151 offset:33792
	ds_read_b128 v[218:221], v151 offset:34816
	ds_read_b128 v[222:225], v151 offset:35840
	ds_read_b128 v[226:229], v151 offset:36864
	ds_read_b128 v[230:233], v151 offset:37888
	ds_read_b128 v[234:237], v151 offset:38912
	ds_read_b128 v[238:241], v151 offset:39936
	global_load_lds_dwordx4 v134, s[34:35]
	s_mov_b32 m0, s49
	s_nop 0
	global_load_lds_dwordx4 v132, s[34:35]
	s_waitcnt vmcnt(8)
	s_waitcnt lgkmcnt(0)
	s_barrier
	s_setprio 1
	s_waitcnt lgkmcnt(0)
	v_mfma_f32_16x16x32_bf16 v[62:65], v[144:147], v[196:199], v[62:65]
	v_mfma_f32_16x16x32_bf16 v[58:61], v[172:175], v[196:199], v[58:61]
	v_mfma_f32_16x16x32_bf16 v[54:57], v[144:147], v[218:221], v[54:57]
	v_mfma_f32_16x16x32_bf16 v[50:53], v[172:175], v[218:221], v[50:53]
	v_mfma_f32_16x16x32_bf16 v[46:49], v[144:147], v[226:229], v[46:49]
	v_mfma_f32_16x16x32_bf16 v[42:45], v[172:175], v[226:229], v[42:45]
	v_mfma_f32_16x16x32_bf16 v[38:41], v[144:147], v[234:237], v[38:41]
	v_mfma_f32_16x16x32_bf16 v[34:37], v[172:175], v[234:237], v[34:37]
	v_mfma_f32_16x16x32_bf16 v[62:65], v[152:155], v[214:217], v[62:65]
	v_mfma_f32_16x16x32_bf16 v[58:61], v[176:179], v[214:217], v[58:61]
	v_mfma_f32_16x16x32_bf16 v[54:57], v[152:155], v[222:225], v[54:57]
	v_mfma_f32_16x16x32_bf16 v[50:53], v[176:179], v[222:225], v[50:53]
	v_mfma_f32_16x16x32_bf16 v[46:49], v[152:155], v[230:233], v[46:49]
	v_mfma_f32_16x16x32_bf16 v[42:45], v[176:179], v[230:233], v[42:45]
	v_mfma_f32_16x16x32_bf16 v[38:41], v[152:155], v[238:241], v[38:41]
	v_mfma_f32_16x16x32_bf16 v[34:37], v[176:179], v[238:241], v[34:37]
	s_setprio 0
	s_setprio 1
	v_mfma_f32_16x16x32_bf16 v[126:129], v[180:183], v[196:199], v[126:129]
	v_mfma_f32_16x16x32_bf16 v[122:125], v[188:191], v[196:199], v[122:125]
	v_mfma_f32_16x16x32_bf16 v[118:121], v[180:183], v[218:221], v[118:121]
	v_mfma_f32_16x16x32_bf16 v[114:117], v[188:191], v[218:221], v[114:117]
	v_mfma_f32_16x16x32_bf16 v[110:113], v[180:183], v[226:229], v[110:113]
	v_mfma_f32_16x16x32_bf16 v[106:109], v[188:191], v[226:229], v[106:109]
	v_mfma_f32_16x16x32_bf16 v[102:105], v[180:183], v[234:237], v[102:105]
	v_mfma_f32_16x16x32_bf16 v[98:101], v[188:191], v[234:237], v[98:101]
	v_mfma_f32_16x16x32_bf16 v[126:129], v[184:187], v[214:217], v[126:129]
	v_mfma_f32_16x16x32_bf16 v[122:125], v[192:195], v[214:217], v[122:125]
	v_mfma_f32_16x16x32_bf16 v[118:121], v[184:187], v[222:225], v[118:121]
	v_mfma_f32_16x16x32_bf16 v[114:117], v[192:195], v[222:225], v[114:117]
	v_mfma_f32_16x16x32_bf16 v[110:113], v[184:187], v[230:233], v[110:113]
	v_mfma_f32_16x16x32_bf16 v[106:109], v[192:195], v[230:233], v[106:109]
	v_mfma_f32_16x16x32_bf16 v[102:105], v[184:187], v[238:241], v[102:105]
	v_mfma_f32_16x16x32_bf16 v[98:101], v[192:195], v[238:241], v[98:101]
	s_setprio 0
	s_barrier
	s_add_u32 s98, s34, 0xfffc0080
	s_addc_u32 s99, s35, -1
	s_add_i32 s34, s64, s2
	s_add_u32 s100, s30, 0x80
	s_addc_u32 s101, s31, 0
	s_mov_b32 m0, s34
	ds_read_b128 v[196:199], v151 offset:49152
	ds_read_b128 v[214:217], v151 offset:50176
	ds_read_b128 v[218:221], v151 offset:51200
	ds_read_b128 v[222:225], v151 offset:52224
	ds_read_b128 v[226:229], v151 offset:53248
	ds_read_b128 v[230:233], v151 offset:54272
	ds_read_b128 v[234:237], v151 offset:55296
	ds_read_b128 v[238:241], v151 offset:56320
	global_load_lds_dwordx4 v0, s[100:101]
	s_add_i32 m0, s34, 0x2000
	s_add_u32 s30, s30, 0x40080
	s_addc_u32 s31, s31, 0
	s_add_i32 s34, s65, s2
	global_load_lds_dwordx4 v130, s[100:101]
	s_mov_b32 m0, s34
	s_nop 0
	global_load_lds_dwordx4 v0, s[30:31]
	s_add_i32 m0, s34, 0x2000
	s_nop 0
	global_load_lds_dwordx4 v130, s[30:31]
	s_mov_b32 m0, s52
	s_nop 0
	global_load_lds_dwordx4 v134, s[98:99]
	s_mov_b32 m0, s53
	s_nop 0
	global_load_lds_dwordx4 v132, s[98:99]
	s_waitcnt vmcnt(8)
	s_waitcnt lgkmcnt(0)
	s_barrier
	s_setprio 1
	s_waitcnt lgkmcnt(0)
	v_mfma_f32_16x16x32_bf16 v[30:33], v[144:147], v[196:199], v[30:33]
	v_mfma_f32_16x16x32_bf16 v[26:29], v[172:175], v[196:199], v[26:29]
	v_mfma_f32_16x16x32_bf16 v[22:25], v[144:147], v[218:221], v[22:25]
	v_mfma_f32_16x16x32_bf16 v[18:21], v[172:175], v[218:221], v[18:21]
	v_mfma_f32_16x16x32_bf16 v[14:17], v[144:147], v[226:229], v[14:17]
	v_mfma_f32_16x16x32_bf16 v[10:13], v[172:175], v[226:229], v[10:13]
	v_mfma_f32_16x16x32_bf16 v[6:9], v[144:147], v[234:237], v[6:9]
	v_mfma_f32_16x16x32_bf16 v[2:5], v[172:175], v[234:237], v[2:5]
	v_mfma_f32_16x16x32_bf16 v[30:33], v[152:155], v[214:217], v[30:33]
	v_mfma_f32_16x16x32_bf16 v[26:29], v[176:179], v[214:217], v[26:29]
	v_mfma_f32_16x16x32_bf16 v[22:25], v[152:155], v[222:225], v[22:25]
	v_mfma_f32_16x16x32_bf16 v[18:21], v[176:179], v[222:225], v[18:21]
	v_mfma_f32_16x16x32_bf16 v[14:17], v[152:155], v[230:233], v[14:17]
	v_mfma_f32_16x16x32_bf16 v[10:13], v[176:179], v[230:233], v[10:13]
	v_mfma_f32_16x16x32_bf16 v[6:9], v[152:155], v[238:241], v[6:9]
	v_mfma_f32_16x16x32_bf16 v[2:5], v[176:179], v[238:241], v[2:5]
	s_setprio 0
	s_setprio 1
	v_mfma_f32_16x16x32_bf16 v[94:97], v[180:183], v[196:199], v[94:97]
	v_mfma_f32_16x16x32_bf16 v[90:93], v[188:191], v[196:199], v[90:93]
	v_mfma_f32_16x16x32_bf16 v[86:89], v[180:183], v[218:221], v[86:89]
	v_mfma_f32_16x16x32_bf16 v[82:85], v[188:191], v[218:221], v[82:85]
	v_mfma_f32_16x16x32_bf16 v[78:81], v[180:183], v[226:229], v[78:81]
	v_mfma_f32_16x16x32_bf16 v[74:77], v[188:191], v[226:229], v[74:77]
	v_mfma_f32_16x16x32_bf16 v[70:73], v[180:183], v[234:237], v[70:73]
	v_mfma_f32_16x16x32_bf16 v[66:69], v[188:191], v[234:237], v[66:69]
	v_mfma_f32_16x16x32_bf16 v[94:97], v[184:187], v[214:217], v[94:97]
	v_mfma_f32_16x16x32_bf16 v[90:93], v[192:195], v[214:217], v[90:93]
	v_mfma_f32_16x16x32_bf16 v[86:89], v[184:187], v[222:225], v[86:89]
	v_mfma_f32_16x16x32_bf16 v[82:85], v[192:195], v[222:225], v[82:85]
	v_mfma_f32_16x16x32_bf16 v[78:81], v[184:187], v[230:233], v[78:81]
	v_mfma_f32_16x16x32_bf16 v[74:77], v[192:195], v[230:233], v[74:77]
	v_mfma_f32_16x16x32_bf16 v[70:73], v[184:187], v[238:241], v[70:73]
	v_mfma_f32_16x16x32_bf16 v[66:69], v[192:195], v[238:241], v[66:69]
	s_setprio 0
	s_barrier
	s_add_i32 s63, s63, 2
	s_add_u32 s28, s28, 0x100
	s_addc_u32 s29, s29, 0
	s_add_u32 s61, s61, 0x100
	s_addc_u32 s62, s62, 0
	s_cmp_gt_u32 s63, 13
	s_cbranch_scc0 .LBB0_330
	s_and_b64 vcc, exec, s[14:15]
	s_cbranch_vccz .LBB0_333
	s_barrier

; #define PG8_STAGE(bufoff, gbase, voff) do { _Pragma("unroll") for (int _i = 0; _i < 2; ++_i) \
;         __builtin_amdgcn_global_load_lds((const unsigned*)((const char*)(gbase) + (voff)[_i]), (PG8_LAS unsigned*)(lds + (bufoff) + ldsw + _i * 8192), 16, 0, 0); } while (0)
; #define PG8_LDA(dst, b, h) do { _Pragma("unroll") for (int m = 0; m < 4; ++m) _Pragma("unroll") for (int k = 0; k < 2; ++k) dst[m][k] = *(const PG8_LAS bf16x8*)(lds + PG8_SA(b, h) + aoff + m * 2048 + k * 1024); } while (0)
; #define PG8_LDB(dst, b, h) do { _Pragma("unroll") for (int n = 0; n < 2; ++n) _Pragma("unroll") for (int k = 0; k < 2; ++k) dst[n][k] = *(const PG8_LAS bf16x8*)(lds + PG8_SB(b, h) + boff + n * 2048 + k * 1024); } while (0)
; #define PG8_MMA(ai, bj, At, Bt) do { __builtin_amdgcn_s_setprio(1); _Pragma("unroll") for (int m = 0; m < 4; ++m) _Pragma("unroll") for (int n = 0; n < 2; ++n) _Pragma("unroll") for (int k = 0; k < 2; ++k) \
;         acc[ai][bj][m][n] = __builtin_amdgcn_mfma_f32_16x16x32_bf16(Bt[n][k], At[m][k], acc[ai][bj][m][n], 0, 0, 0); __builtin_amdgcn_s_setprio(0); } while (0)
; #define PG8_WAIT_V(n) asm volatile("s_waitcnt vmcnt(" #n ")" ::: "memory")
; #define PG8_WAIT_L(n) asm volatile("s_waitcnt lgkmcnt(" #n ")" ::: "memory")
; #define PG8_BAR __builtin_amdgcn_s_barrier()
; #define PG8_SCHED __builtin_amdgcn_sched_barrier(0)
; template <class Epi, class Sched, bool ALIGN_EPI = false, bool SP2 = false>
; __device__ __forceinline__ void gemm_phase(PG8_LAS unsigned char* lds, const Gemm g, const Sched& S, const Epi& E) {
;     ...
;             PG8_LDB(B0, 0, 0); PG8_LDB(B1, 0, 1); PG8_SCHED; PG8_LDA(At, 0, 0); PG8_STAGE(PG8_SA(1, 1), a1 + hstep, voffA);
;             PG8_WAIT_V(8); PG8_WAIT_L(0); PG8_BAR; PG8_MMA(0, 0, At, B0); PG8_MMA(0, 1, At, B1); PG8_BAR; PG8_SCHED;
;             PG8_LDA(At, 0, 1); PG8_STAGE(PG8_SB(0, 0), b2, voffB); PG8_STAGE(PG8_SB(0, 1), b2 + hstep, voffB); PG8_STAGE(PG8_SA(0, 0), a2, voffA);
;             PG8_WAIT_V(8); PG8_WAIT_L(0); PG8_BAR; PG8_MMA(1, 0, At, B0); PG8_MMA(1, 1, At, B1); PG8_BAR; PG8_SCHED;
;             PG8_LDB(B0, 1, 0); PG8_LDB(B1, 1, 1); PG8_SCHED; PG8_LDA(At, 1, 0); PG8_STAGE(PG8_SA(0, 1), a2 + hstep, voffA);
.LBB0_458:
	s_add_u32 s47, s20, 0x100
	s_addc_u32 s48, s21, 0
	s_mov_b32 s49, -2
	s_waitcnt lgkmcnt(0)
	s_waitcnt vmcnt(0)
	s_add_u32 s20, s18, 0x100
	s_addc_u32 s21, s19, 0
	s_add_i32 s50, 0, 0x10000
	s_cmp_eq_u32 s49, 40
	s_cselect_b32 s25, s9, s21
	s_cselect_b32 s24, s8, s20
	s_cselect_b32 s23, s17, s48
	s_cselect_b32 s22, s16, s47
	s_add_i32 s51, 0, 0x14000
	v_add_u32_e32 v142, s50, v165
	v_add_u32_e32 v182, s51, v165
	ds_read_b128 v[130:133], v142
	ds_read_b128 v[134:137], v142 offset:1024
	ds_read_b128 v[138:141], v142 offset:2048
	ds_read_b128 v[142:145], v142 offset:3072
	ds_read_b128 v[146:149], v182
	ds_read_b128 v[150:153], v182 offset:1024
	ds_read_b128 v[154:157], v182 offset:2048
	ds_read_b128 v[182:185], v182 offset:3072
	s_add_i32 m0, s28, 0xc000
	ds_read_b128 v[186:189], v214
	ds_read_b128 v[190:193], v214 offset:1024
	ds_read_b128 v[194:197], v214 offset:2048
	ds_read_b128 v[216:219], v214 offset:3072
	ds_read_b128 v[220:223], v214 offset:4096
	ds_read_b128 v[224:227], v214 offset:5120
	ds_read_b128 v[228:231], v214 offset:6144
	ds_read_b128 v[232:235], v214 offset:7168
	global_load_lds_dwordx4 v178, s[18:19]
	s_add_i32 m0, s28, 0xe000
	s_nop 0
	global_load_lds_dwordx4 v180, s[18:19]
	s_waitcnt vmcnt(8)
	s_waitcnt lgkmcnt(0)
	s_barrier
	s_setprio 1
	s_waitcnt lgkmcnt(0)
	v_mfma_f32_16x16x32_bf16 v[126:129], v[130:133], v[186:189], 0
	v_mfma_f32_16x16x32_bf16 v[122:125], v[138:141], v[186:189], 0
	v_mfma_f32_16x16x32_bf16 v[110:113], v[130:133], v[194:197], 0
	v_mfma_f32_16x16x32_bf16 v[106:109], v[138:141], v[194:197], 0
	v_mfma_f32_16x16x32_bf16 v[94:97], v[130:133], v[220:223], 0
	v_mfma_f32_16x16x32_bf16 v[90:93], v[138:141], v[220:223], 0
	v_mfma_f32_16x16x32_bf16 v[78:81], v[130:133], v[228:231], 0
	v_mfma_f32_16x16x32_bf16 v[74:77], v[138:141], v[228:231], 0
	v_mfma_f32_16x16x32_bf16 v[126:129], v[134:137], v[190:193], v[126:129]
	v_mfma_f32_16x16x32_bf16 v[122:125], v[142:145], v[190:193], v[122:125]
	v_mfma_f32_16x16x32_bf16 v[110:113], v[134:137], v[216:219], v[110:113]
	v_mfma_f32_16x16x32_bf16 v[106:109], v[142:145], v[216:219], v[106:109]
	v_mfma_f32_16x16x32_bf16 v[94:97], v[134:137], v[224:227], v[94:97]
	v_mfma_f32_16x16x32_bf16 v[90:93], v[142:145], v[224:227], v[90:93]
	v_mfma_f32_16x16x32_bf16 v[78:81], v[134:137], v[232:235], v[78:81]
	v_mfma_f32_16x16x32_bf16 v[74:77], v[142:145], v[232:235], v[74:77]
	s_setprio 0
	s_setprio 1
	v_mfma_f32_16x16x32_bf16 v[118:121], v[146:149], v[186:189], 0
	v_mfma_f32_16x16x32_bf16 v[114:117], v[154:157], v[186:189], 0
	v_mfma_f32_16x16x32_bf16 v[102:105], v[146:149], v[194:197], 0
	v_mfma_f32_16x16x32_bf16 v[98:101], v[154:157], v[194:197], 0
	v_mfma_f32_16x16x32_bf16 v[86:89], v[146:149], v[220:223], 0
	v_mfma_f32_16x16x32_bf16 v[82:85], v[154:157], v[220:223], 0
	v_mfma_f32_16x16x32_bf16 v[70:73], v[146:149], v[228:231], 0
	v_mfma_f32_16x16x32_bf16 v[66:69], v[154:157], v[228:231], 0
	v_mfma_f32_16x16x32_bf16 v[118:121], v[150:153], v[190:193], v[118:121]
	v_mfma_f32_16x16x32_bf16 v[114:117], v[182:185], v[190:193], v[114:117]
	v_mfma_f32_16x16x32_bf16 v[102:105], v[150:153], v[216:219], v[102:105]
	v_mfma_f32_16x16x32_bf16 v[98:101], v[182:185], v[216:219], v[98:101]
	v_mfma_f32_16x16x32_bf16 v[86:89], v[150:153], v[224:227], v[86:89]
	v_mfma_f32_16x16x32_bf16 v[82:85], v[182:185], v[224:227], v[82:85]
	v_mfma_f32_16x16x32_bf16 v[70:73], v[150:153], v[232:235], v[70:73]
	v_mfma_f32_16x16x32_bf16 v[66:69], v[182:185], v[232:235], v[66:69]
	s_setprio 0
	s_barrier
	s_add_i32 s18, s50, s2
	s_mov_b32 m0, s18
	ds_read_b128 v[186:189], v214 offset:16384
	ds_read_b128 v[190:193], v214 offset:17408
	ds_read_b128 v[194:197], v214 offset:18432
	ds_read_b128 v[216:219], v214 offset:19456
	ds_read_b128 v[220:223], v214 offset:20480
	ds_read_b128 v[224:227], v214 offset:21504
	ds_read_b128 v[228:231], v214 offset:22528
	ds_read_b128 v[232:235], v214 offset:23552
	global_load_lds_dwordx4 v0, s[22:23]
	s_add_i32 m0, s18, 0x2000
	s_add_u32 s18, s22, 0xb0000
	s_addc_u32 s19, s23, 0
	s_add_i32 s50, s51, s2
	global_load_lds_dwordx4 v172, s[22:23]
	s_mov_b32 m0, s50
	s_nop 0
	global_load_lds_dwordx4 v0, s[18:19]
	s_add_i32 m0, s50, 0x2000
	s_nop 0
	global_load_lds_dwordx4 v172, s[18:19]
	s_mov_b32 m0, s28
	s_nop 0
	global_load_lds_dwordx4 v176, s[24:25]
	s_mov_b32 m0, s29
	s_nop 0
	global_load_lds_dwordx4 v174, s[24:25]
	s_waitcnt vmcnt(8)
	s_waitcnt lgkmcnt(0)
	s_barrier
	s_setprio 1
	s_waitcnt lgkmcnt(0)
	v_mfma_f32_16x16x32_bf16 v[62:65], v[130:133], v[186:189], 0
	v_mfma_f32_16x16x32_bf16 v[58:61], v[138:141], v[186:189], 0
	v_mfma_f32_16x16x32_bf16 v[46:49], v[130:133], v[194:197], 0
	v_mfma_f32_16x16x32_bf16 v[42:45], v[138:141], v[194:197], 0
	v_mfma_f32_16x16x32_bf16 v[30:33], v[130:133], v[220:223], 0
	v_mfma_f32_16x16x32_bf16 v[26:29], v[138:141], v[220:223], 0
	v_mfma_f32_16x16x32_bf16 v[14:17], v[130:133], v[228:231], 0
	v_mfma_f32_16x16x32_bf16 v[10:13], v[138:141], v[228:231], 0
	v_mfma_f32_16x16x32_bf16 v[62:65], v[134:137], v[190:193], v[62:65]
	v_mfma_f32_16x16x32_bf16 v[58:61], v[142:145], v[190:193], v[58:61]
	v_mfma_f32_16x16x32_bf16 v[46:49], v[134:137], v[216:219], v[46:49]
	v_mfma_f32_16x16x32_bf16 v[42:45], v[142:145], v[216:219], v[42:45]
	v_mfma_f32_16x16x32_bf16 v[30:33], v[134:137], v[224:227], v[30:33]
	v_mfma_f32_16x16x32_bf16 v[26:29], v[142:145], v[224:227], v[26:29]
	v_mfma_f32_16x16x32_bf16 v[14:17], v[134:137], v[232:235], v[14:17]
	v_mfma_f32_16x16x32_bf16 v[10:13], v[142:145], v[232:235], v[10:13]
	s_setprio 0
	s_setprio 1
	v_mfma_f32_16x16x32_bf16 v[54:57], v[146:149], v[186:189], 0
	v_mfma_f32_16x16x32_bf16 v[50:53], v[154:157], v[186:189], 0
	v_mfma_f32_16x16x32_bf16 v[38:41], v[146:149], v[194:197], 0
	v_mfma_f32_16x16x32_bf16 v[34:37], v[154:157], v[194:197], 0
	v_mfma_f32_16x16x32_bf16 v[22:25], v[146:149], v[220:223], 0
	v_mfma_f32_16x16x32_bf16 v[18:21], v[154:157], v[220:223], 0
	v_mfma_f32_16x16x32_bf16 v[6:9], v[146:149], v[228:231], 0
	v_mfma_f32_16x16x32_bf16 v[2:5], v[154:157], v[228:231], 0
	v_mfma_f32_16x16x32_bf16 v[54:57], v[150:153], v[190:193], v[54:57]
	v_mfma_f32_16x16x32_bf16 v[50:53], v[182:185], v[190:193], v[50:53]
	v_mfma_f32_16x16x32_bf16 v[38:41], v[150:153], v[216:219], v[38:41]
	v_mfma_f32_16x16x32_bf16 v[34:37], v[182:185], v[216:219], v[34:37]
	v_mfma_f32_16x16x32_bf16 v[22:25], v[150:153], v[224:227], v[22:25]
	v_mfma_f32_16x16x32_bf16 v[18:21], v[182:185], v[224:227], v[18:21]
	v_mfma_f32_16x16x32_bf16 v[6:9], v[150:153], v[232:235], v[6:9]
	v_mfma_f32_16x16x32_bf16 v[2:5], v[182:185], v[232:235], v[2:5]
	s_setprio 0
	s_barrier
; #define PG8_STAGE(bufoff, gbase, voff) do { _Pragma("unroll") for (int _i = 0; _i < 2; ++_i) \
;         __builtin_amdgcn_global_load_lds((const unsigned*)((const char*)(gbase) + (voff)[_i]), (PG8_LAS unsigned*)(lds + (bufoff) + ldsw + _i * 8192), 16, 0, 0); } while (0)
; #define PG8_LDA(dst, b, h) do { _Pragma("unroll") for (int m = 0; m < 4; ++m) _Pragma("unroll") for (int k = 0; k < 2; ++k) dst[m][k] = *(const PG8_LAS bf16x8*)(lds + PG8_SA(b, h) + aoff + m * 2048 + k * 1024); } while (0)
; #define PG8_LDB(dst, b, h) do { _Pragma("unroll") for (int n = 0; n < 2; ++n) _Pragma("unroll") for (int k = 0; k < 2; ++k) dst[n][k] = *(const PG8_LAS bf16x8*)(lds + PG8_SB(b, h) + boff + n * 2048 + k * 1024); } while (0)
; #define PG8_MMA(ai, bj, At, Bt) do { __builtin_amdgcn_s_setprio(1); _Pragma("unroll") for (int m = 0; m < 4; ++m) _Pragma("unroll") for (int n = 0; n < 2; ++n) _Pragma("unroll") for (int k = 0; k < 2; ++k) \
;         acc[ai][bj][m][n] = __builtin_amdgcn_mfma_f32_16x16x32_bf16(Bt[n][k], At[m][k], acc[ai][bj][m][n], 0, 0, 0); __builtin_amdgcn_s_setprio(0); } while (0)
; #define PG8_WAIT_V(n) asm volatile("s_waitcnt vmcnt(" #n ")" ::: "memory")
; #define PG8_WAIT_L(n) asm volatile("s_waitcnt lgkmcnt(" #n ")" ::: "memory")
; #define PG8_BAR __builtin_amdgcn_s_barrier()
; #define PG8_SCHED __builtin_amdgcn_sched_barrier(0)
; template <class Epi, class Sched, bool ALIGN_EPI = false, bool SP2 = false>
; __device__ __forceinline__ void gemm_phase(PG8_LAS unsigned char* lds, const Gemm g, const Sched& S, const Epi& E) {
;     ...
;             PG8_LDB(B0, 1, 0); PG8_LDB(B1, 1, 1); PG8_SCHED; PG8_LDA(At, 1, 0); PG8_STAGE(PG8_SA(0, 1), a2 + hstep, voffA);
;             PG8_WAIT_V(8); PG8_WAIT_L(0); PG8_BAR; PG8_MMA(0, 0, At, B0); PG8_MMA(0, 1, At, B1); PG8_BAR; PG8_SCHED;
;             PG8_LDA(At, 1, 1); PG8_STAGE(PG8_SB(1, 0), b3, voffB); PG8_STAGE(PG8_SB(1, 1), b3 + hstep, voffB); PG8_STAGE(PG8_SA(1, 0), a3, voffA);
;             PG8_WAIT_V(8); PG8_WAIT_L(0); PG8_BAR; PG8_MMA(1, 0, At, B0); PG8_MMA(1, 1, At, B1); PG8_BAR; PG8_SCHED;
	s_add_i32 s50, 0, 0x18000
	s_add_i32 s51, 0, 0x1c000
	v_add_u32_e32 v142, s50, v165
	v_add_u32_e32 v182, s51, v165
	ds_read_b128 v[130:133], v142
	ds_read_b128 v[134:137], v142 offset:1024
	ds_read_b128 v[138:141], v142 offset:2048
	ds_read_b128 v[142:145], v142 offset:3072
	ds_read_b128 v[146:149], v182
	ds_read_b128 v[150:153], v182 offset:1024
	ds_read_b128 v[154:157], v182 offset:2048
	ds_read_b128 v[182:185], v182 offset:3072
	s_add_u32 s18, s24, 0xb0000
	s_addc_u32 s19, s25, 0
	s_mov_b32 m0, s30
	ds_read_b128 v[186:189], v214 offset:32768
	ds_read_b128 v[190:193], v214 offset:33792
	ds_read_b128 v[194:197], v214 offset:34816
	ds_read_b128 v[216:219], v214 offset:35840
	ds_read_b128 v[220:223], v214 offset:36864
	ds_read_b128 v[224:227], v214 offset:37888
	ds_read_b128 v[228:231], v214 offset:38912
	ds_read_b128 v[232:235], v214 offset:39936
	global_load_lds_dwordx4 v176, s[18:19]
	s_mov_b32 m0, s31
	s_nop 0
	global_load_lds_dwordx4 v174, s[18:19]
	s_waitcnt vmcnt(8)
	s_waitcnt lgkmcnt(0)
	s_barrier
	s_setprio 1
	s_waitcnt lgkmcnt(0)
	v_mfma_f32_16x16x32_bf16 v[126:129], v[130:133], v[186:189], v[126:129]
	v_mfma_f32_16x16x32_bf16 v[122:125], v[138:141], v[186:189], v[122:125]
	v_mfma_f32_16x16x32_bf16 v[110:113], v[130:133], v[194:197], v[110:113]
	v_mfma_f32_16x16x32_bf16 v[106:109], v[138:141], v[194:197], v[106:109]
	v_mfma_f32_16x16x32_bf16 v[94:97], v[130:133], v[220:223], v[94:97]
	v_mfma_f32_16x16x32_bf16 v[90:93], v[138:141], v[220:223], v[90:93]
	v_mfma_f32_16x16x32_bf16 v[78:81], v[130:133], v[228:231], v[78:81]
	v_mfma_f32_16x16x32_bf16 v[74:77], v[138:141], v[228:231], v[74:77]
	v_mfma_f32_16x16x32_bf16 v[126:129], v[134:137], v[190:193], v[126:129]
	v_mfma_f32_16x16x32_bf16 v[122:125], v[142:145], v[190:193], v[122:125]
	v_mfma_f32_16x16x32_bf16 v[110:113], v[134:137], v[216:219], v[110:113]
	v_mfma_f32_16x16x32_bf16 v[106:109], v[142:145], v[216:219], v[106:109]
	v_mfma_f32_16x16x32_bf16 v[94:97], v[134:137], v[224:227], v[94:97]
	v_mfma_f32_16x16x32_bf16 v[90:93], v[142:145], v[224:227], v[90:93]
	v_mfma_f32_16x16x32_bf16 v[78:81], v[134:137], v[232:235], v[78:81]
	v_mfma_f32_16x16x32_bf16 v[74:77], v[142:145], v[232:235], v[74:77]
	s_setprio 0
	s_setprio 1
	v_mfma_f32_16x16x32_bf16 v[118:121], v[146:149], v[186:189], v[118:121]
	v_mfma_f32_16x16x32_bf16 v[114:117], v[154:157], v[186:189], v[114:117]
	v_mfma_f32_16x16x32_bf16 v[102:105], v[146:149], v[194:197], v[102:105]
	v_mfma_f32_16x16x32_bf16 v[98:101], v[154:157], v[194:197], v[98:101]
	v_mfma_f32_16x16x32_bf16 v[86:89], v[146:149], v[220:223], v[86:89]
	v_mfma_f32_16x16x32_bf16 v[82:85], v[154:157], v[220:223], v[82:85]
	v_mfma_f32_16x16x32_bf16 v[70:73], v[146:149], v[228:231], v[70:73]
	v_mfma_f32_16x16x32_bf16 v[66:69], v[154:157], v[228:231], v[66:69]
	v_mfma_f32_16x16x32_bf16 v[118:121], v[150:153], v[190:193], v[118:121]
	v_mfma_f32_16x16x32_bf16 v[114:117], v[182:185], v[190:193], v[114:117]
	v_mfma_f32_16x16x32_bf16 v[102:105], v[150:153], v[216:219], v[102:105]
	v_mfma_f32_16x16x32_bf16 v[98:101], v[182:185], v[216:219], v[98:101]
	v_mfma_f32_16x16x32_bf16 v[86:89], v[150:153], v[224:227], v[86:89]
	v_mfma_f32_16x16x32_bf16 v[82:85], v[182:185], v[224:227], v[82:85]
	v_mfma_f32_16x16x32_bf16 v[70:73], v[150:153], v[232:235], v[70:73]
	v_mfma_f32_16x16x32_bf16 v[66:69], v[182:185], v[232:235], v[66:69]
	s_setprio 0
	s_barrier
	s_add_i32 s18, s50, s2
	s_add_u32 s98, s22, 0x80
	s_addc_u32 s99, s23, 0
	s_add_u32 s100, s24, 0x80
	s_addc_u32 s101, s25, 0
	s_mov_b32 m0, s18
	ds_read_b128 v[186:189], v214 offset:49152
	ds_read_b128 v[190:193], v214 offset:50176
	ds_read_b128 v[194:197], v214 offset:51200
	ds_read_b128 v[216:219], v214 offset:52224
	ds_read_b128 v[220:223], v214 offset:53248
	ds_read_b128 v[224:227], v214 offset:54272
	ds_read_b128 v[228:231], v214 offset:55296
	ds_read_b128 v[232:235], v214 offset:56320
	global_load_lds_dwordx4 v0, s[98:99]
	s_add_i32 m0, s18, 0x2000
	s_add_u32 s18, s22, 0xb0080
	s_addc_u32 s19, s23, 0
	s_add_i32 s22, s51, s2
	global_load_lds_dwordx4 v172, s[98:99]
	s_mov_b32 m0, s22
	s_nop 0
	global_load_lds_dwordx4 v0, s[18:19]
	s_add_i32 m0, s22, 0x2000
	s_nop 0
	global_load_lds_dwordx4 v172, s[18:19]
	s_mov_b32 m0, s35
	s_nop 0
	global_load_lds_dwordx4 v176, s[100:101]
	s_mov_b32 m0, s37
	s_nop 0
	global_load_lds_dwordx4 v174, s[100:101]
	s_waitcnt vmcnt(8)
	s_waitcnt lgkmcnt(0)
	s_barrier
	s_setprio 1
	s_waitcnt lgkmcnt(0)
	v_mfma_f32_16x16x32_bf16 v[62:65], v[130:133], v[186:189], v[62:65]
	v_mfma_f32_16x16x32_bf16 v[58:61], v[138:141], v[186:189], v[58:61]
	v_mfma_f32_16x16x32_bf16 v[46:49], v[130:133], v[194:197], v[46:49]
	v_mfma_f32_16x16x32_bf16 v[42:45], v[138:141], v[194:197], v[42:45]
	v_mfma_f32_16x16x32_bf16 v[30:33], v[130:133], v[220:223], v[30:33]
	v_mfma_f32_16x16x32_bf16 v[26:29], v[138:141], v[220:223], v[26:29]
	v_mfma_f32_16x16x32_bf16 v[14:17], v[130:133], v[228:231], v[14:17]
	v_mfma_f32_16x16x32_bf16 v[10:13], v[138:141], v[228:231], v[10:13]
	v_mfma_f32_16x16x32_bf16 v[62:65], v[134:137], v[190:193], v[62:65]
	v_mfma_f32_16x16x32_bf16 v[58:61], v[142:145], v[190:193], v[58:61]
	v_mfma_f32_16x16x32_bf16 v[46:49], v[134:137], v[216:219], v[46:49]
	v_mfma_f32_16x16x32_bf16 v[42:45], v[142:145], v[216:219], v[42:45]
	v_mfma_f32_16x16x32_bf16 v[30:33], v[134:137], v[224:227], v[30:33]
	v_mfma_f32_16x16x32_bf16 v[26:29], v[142:145], v[224:227], v[26:29]
	v_mfma_f32_16x16x32_bf16 v[14:17], v[134:137], v[232:235], v[14:17]
	v_mfma_f32_16x16x32_bf16 v[10:13], v[142:145], v[232:235], v[10:13]
	s_setprio 0
	s_setprio 1
	v_mfma_f32_16x16x32_bf16 v[54:57], v[146:149], v[186:189], v[54:57]
	v_mfma_f32_16x16x32_bf16 v[50:53], v[154:157], v[186:189], v[50:53]
	v_mfma_f32_16x16x32_bf16 v[38:41], v[146:149], v[194:197], v[38:41]
	v_mfma_f32_16x16x32_bf16 v[34:37], v[154:157], v[194:197], v[34:37]
	v_mfma_f32_16x16x32_bf16 v[22:25], v[146:149], v[220:223], v[22:25]
	v_mfma_f32_16x16x32_bf16 v[18:21], v[154:157], v[220:223], v[18:21]
	v_mfma_f32_16x16x32_bf16 v[6:9], v[146:149], v[228:231], v[6:9]
	v_mfma_f32_16x16x32_bf16 v[2:5], v[154:157], v[228:231], v[2:5]
	v_mfma_f32_16x16x32_bf16 v[54:57], v[150:153], v[190:193], v[54:57]
	v_mfma_f32_16x16x32_bf16 v[50:53], v[182:185], v[190:193], v[50:53]
	v_mfma_f32_16x16x32_bf16 v[38:41], v[150:153], v[216:219], v[38:41]
	v_mfma_f32_16x16x32_bf16 v[34:37], v[182:185], v[216:219], v[34:37]
	v_mfma_f32_16x16x32_bf16 v[22:25], v[150:153], v[224:227], v[22:25]
	v_mfma_f32_16x16x32_bf16 v[18:21], v[182:185], v[224:227], v[18:21]
	v_mfma_f32_16x16x32_bf16 v[6:9], v[150:153], v[232:235], v[6:9]
	v_mfma_f32_16x16x32_bf16 v[2:5], v[182:185], v[232:235], v[2:5]
	s_setprio 0
	s_barrier
	s_add_i32 s49, s49, 2
	s_add_u32 s47, s47, 0x100
	s_addc_u32 s48, s48, 0
	s_mov_b64 s[18:19], s[20:21]
; #define PG8_STAGE(bufoff, gbase, voff) do { _Pragma("unroll") for (int _i = 0; _i < 2; ++_i) \
;         __builtin_amdgcn_global_load_lds((const unsigned*)((const char*)(gbase) + (voff)[_i]), (PG8_LAS unsigned*)(lds + (bufoff) + ldsw + _i * 8192), 16, 0, 0); } while (0)
; #define PG8_LDA(dst, b, h) do { _Pragma("unroll") for (int m = 0; m < 4; ++m) _Pragma("unroll") for (int k = 0; k < 2; ++k) dst[m][k] = *(const PG8_LAS bf16x8*)(lds + PG8_SA(b, h) + aoff + m * 2048 + k * 1024); } while (0)
; #define PG8_LDB(dst, b, h) do { _Pragma("unroll") for (int n = 0; n < 2; ++n) _Pragma("unroll") for (int k = 0; k < 2; ++k) dst[n][k] = *(const PG8_LAS bf16x8*)(lds + PG8_SB(b, h) + boff + n * 2048 + k * 1024); } while (0)
; #define PG8_MMA(ai, bj, At, Bt) do { __builtin_amdgcn_s_setprio(1); _Pragma("unroll") for (int m = 0; m < 4; ++m) _Pragma("unroll") for (int n = 0; n < 2; ++n) _Pragma("unroll") for (int k = 0; k < 2; ++k) \
;         acc[ai][bj][m][n] = __builtin_amdgcn_mfma_f32_16x16x32_bf16(Bt[n][k], At[m][k], acc[ai][bj][m][n], 0, 0, 0); __builtin_amdgcn_s_setprio(0); } while (0)
; #define PG8_WAIT_V(n) asm volatile("s_waitcnt vmcnt(" #n ")" ::: "memory")
; #define PG8_WAIT_L(n) asm volatile("s_waitcnt lgkmcnt(" #n ")" ::: "memory")
; #define PG8_BAR __builtin_amdgcn_s_barrier()
; #define PG8_SCHED __builtin_amdgcn_sched_barrier(0)
; template <class Epi, class Sched, bool ALIGN_EPI = false, bool SP2 = false>
; __device__ __forceinline__ void gemm_phase(PG8_LAS unsigned char* lds, const Gemm g, const Sched& S, const Epi& E) {
;     ...
;             PG8_LDB(B0, 0, 0); PG8_LDB(B1, 0, 1); PG8_SCHED; PG8_LDA(At, 0, 0); PG8_STAGE(PG8_SA(1, 1), a1 + hstep, voffA);
;             PG8_WAIT_V(8); PG8_WAIT_L(0); PG8_BAR; PG8_MMA(0, 0, At, B0); PG8_MMA(0, 1, At, B1); PG8_BAR; PG8_SCHED;
;             PG8_LDA(At, 0, 1); PG8_STAGE(PG8_SB(0, 0), b2, voffB); PG8_STAGE(PG8_SB(0, 1), b2 + hstep, voffB); PG8_STAGE(PG8_SA(0, 0), a2, voffA);
;             PG8_WAIT_V(8); PG8_WAIT_L(0); PG8_BAR; PG8_MMA(1, 0, At, B0); PG8_MMA(1, 1, At, B1); PG8_BAR; PG8_SCHED;
;             PG8_LDB(B0, 1, 0); PG8_LDB(B1, 1, 1); PG8_SCHED; PG8_LDA(At, 1, 0); PG8_STAGE(PG8_SA(0, 1), a2 + hstep, voffA);
.LBB0_459:
	s_add_u32 s20, s18, 0x100
	s_addc_u32 s21, s19, 0
	s_add_i32 s50, 0, 0x10000
	s_cmp_eq_u32 s49, 40
	s_cselect_b32 s25, s9, s21
	s_cselect_b32 s24, s8, s20
	s_cselect_b32 s23, s17, s48
	s_cselect_b32 s22, s16, s47
	s_add_i32 s51, 0, 0x14000
	v_add_u32_e32 v142, s50, v165
	v_add_u32_e32 v182, s51, v165
	ds_read_b128 v[130:133], v142
	ds_read_b128 v[134:137], v142 offset:1024
	ds_read_b128 v[138:141], v142 offset:2048
	ds_read_b128 v[142:145], v142 offset:3072
	ds_read_b128 v[146:149], v182
	ds_read_b128 v[150:153], v182 offset:1024
	ds_read_b128 v[154:157], v182 offset:2048
	ds_read_b128 v[182:185], v182 offset:3072
	s_add_i32 m0, s28, 0xc000
	ds_read_b128 v[186:189], v214
	ds_read_b128 v[190:193], v214 offset:1024
	ds_read_b128 v[194:197], v214 offset:2048
	ds_read_b128 v[216:219], v214 offset:3072
	ds_read_b128 v[220:223], v214 offset:4096
	ds_read_b128 v[224:227], v214 offset:5120
	ds_read_b128 v[228:231], v214 offset:6144
	ds_read_b128 v[232:235], v214 offset:7168
	global_load_lds_dwordx4 v178, s[18:19]
	s_add_i32 m0, s28, 0xe000
	s_nop 0
	global_load_lds_dwordx4 v180, s[18:19]
	s_waitcnt vmcnt(8)
	s_waitcnt lgkmcnt(0)
	s_barrier
	s_setprio 1
	s_waitcnt lgkmcnt(0)
	v_mfma_f32_16x16x32_bf16 v[126:129], v[130:133], v[186:189], v[126:129]
	v_mfma_f32_16x16x32_bf16 v[122:125], v[138:141], v[186:189], v[122:125]
	v_mfma_f32_16x16x32_bf16 v[110:113], v[130:133], v[194:197], v[110:113]
	v_mfma_f32_16x16x32_bf16 v[106:109], v[138:141], v[194:197], v[106:109]
	v_mfma_f32_16x16x32_bf16 v[94:97], v[130:133], v[220:223], v[94:97]
	v_mfma_f32_16x16x32_bf16 v[90:93], v[138:141], v[220:223], v[90:93]
	v_mfma_f32_16x16x32_bf16 v[78:81], v[130:133], v[228:231], v[78:81]
	v_mfma_f32_16x16x32_bf16 v[74:77], v[138:141], v[228:231], v[74:77]
	v_mfma_f32_16x16x32_bf16 v[126:129], v[134:137], v[190:193], v[126:129]
	v_mfma_f32_16x16x32_bf16 v[122:125], v[142:145], v[190:193], v[122:125]
	v_mfma_f32_16x16x32_bf16 v[110:113], v[134:137], v[216:219], v[110:113]
	v_mfma_f32_16x16x32_bf16 v[106:109], v[142:145], v[216:219], v[106:109]
	v_mfma_f32_16x16x32_bf16 v[94:97], v[134:137], v[224:227], v[94:97]
	v_mfma_f32_16x16x32_bf16 v[90:93], v[142:145], v[224:227], v[90:93]
	v_mfma_f32_16x16x32_bf16 v[78:81], v[134:137], v[232:235], v[78:81]
	v_mfma_f32_16x16x32_bf16 v[74:77], v[142:145], v[232:235], v[74:77]
	s_setprio 0
	s_setprio 1
	v_mfma_f32_16x16x32_bf16 v[118:121], v[146:149], v[186:189], v[118:121]
	v_mfma_f32_16x16x32_bf16 v[114:117], v[154:157], v[186:189], v[114:117]
	v_mfma_f32_16x16x32_bf16 v[102:105], v[146:149], v[194:197], v[102:105]
	v_mfma_f32_16x16x32_bf16 v[98:101], v[154:157], v[194:197], v[98:101]
	v_mfma_f32_16x16x32_bf16 v[86:89], v[146:149], v[220:223], v[86:89]
	v_mfma_f32_16x16x32_bf16 v[82:85], v[154:157], v[220:223], v[82:85]
	v_mfma_f32_16x16x32_bf16 v[70:73], v[146:149], v[228:231], v[70:73]
	v_mfma_f32_16x16x32_bf16 v[66:69], v[154:157], v[228:231], v[66:69]
	v_mfma_f32_16x16x32_bf16 v[118:121], v[150:153], v[190:193], v[118:121]
	v_mfma_f32_16x16x32_bf16 v[114:117], v[182:185], v[190:193], v[114:117]
	v_mfma_f32_16x16x32_bf16 v[102:105], v[150:153], v[216:219], v[102:105]
	v_mfma_f32_16x16x32_bf16 v[98:101], v[182:185], v[216:219], v[98:101]
	v_mfma_f32_16x16x32_bf16 v[86:89], v[150:153], v[224:227], v[86:89]
	v_mfma_f32_16x16x32_bf16 v[82:85], v[182:185], v[224:227], v[82:85]
	v_mfma_f32_16x16x32_bf16 v[70:73], v[150:153], v[232:235], v[70:73]
	v_mfma_f32_16x16x32_bf16 v[66:69], v[182:185], v[232:235], v[66:69]
	s_setprio 0
	s_barrier
	s_add_i32 s18, s50, s2
	s_mov_b32 m0, s18
	ds_read_b128 v[186:189], v214 offset:16384
	ds_read_b128 v[190:193], v214 offset:17408
	ds_read_b128 v[194:197], v214 offset:18432
	ds_read_b128 v[216:219], v214 offset:19456
	ds_read_b128 v[220:223], v214 offset:20480
	ds_read_b128 v[224:227], v214 offset:21504
	ds_read_b128 v[228:231], v214 offset:22528
	ds_read_b128 v[232:235], v214 offset:23552
	global_load_lds_dwordx4 v0, s[22:23]
	s_add_i32 m0, s18, 0x2000
	s_add_u32 s18, s22, 0xb0000
	s_addc_u32 s19, s23, 0
	s_add_i32 s50, s51, s2
	global_load_lds_dwordx4 v172, s[22:23]
	s_mov_b32 m0, s50
	s_nop 0
	global_load_lds_dwordx4 v0, s[18:19]
	s_add_i32 m0, s50, 0x2000
	s_nop 0
	global_load_lds_dwordx4 v172, s[18:19]
	s_mov_b32 m0, s28
	s_nop 0
	global_load_lds_dwordx4 v176, s[24:25]
	s_mov_b32 m0, s29
	s_nop 0
	global_load_lds_dwordx4 v174, s[24:25]
	s_waitcnt vmcnt(8)
	s_waitcnt lgkmcnt(0)
	s_barrier
	s_setprio 1
	s_waitcnt lgkmcnt(0)
	v_mfma_f32_16x16x32_bf16 v[62:65], v[130:133], v[186:189], v[62:65]
	v_mfma_f32_16x16x32_bf16 v[58:61], v[138:141], v[186:189], v[58:61]
	v_mfma_f32_16x16x32_bf16 v[46:49], v[130:133], v[194:197], v[46:49]
	v_mfma_f32_16x16x32_bf16 v[42:45], v[138:141], v[194:197], v[42:45]
	v_mfma_f32_16x16x32_bf16 v[30:33], v[130:133], v[220:223], v[30:33]
	v_mfma_f32_16x16x32_bf16 v[26:29], v[138:141], v[220:223], v[26:29]
	v_mfma_f32_16x16x32_bf16 v[14:17], v[130:133], v[228:231], v[14:17]
	v_mfma_f32_16x16x32_bf16 v[10:13], v[138:141], v[228:231], v[10:13]
	v_mfma_f32_16x16x32_bf16 v[62:65], v[134:137], v[190:193], v[62:65]
	v_mfma_f32_16x16x32_bf16 v[58:61], v[142:145], v[190:193], v[58:61]
	v_mfma_f32_16x16x32_bf16 v[46:49], v[134:137], v[216:219], v[46:49]
	v_mfma_f32_16x16x32_bf16 v[42:45], v[142:145], v[216:219], v[42:45]
	v_mfma_f32_16x16x32_bf16 v[30:33], v[134:137], v[224:227], v[30:33]
	v_mfma_f32_16x16x32_bf16 v[26:29], v[142:145], v[224:227], v[26:29]
	v_mfma_f32_16x16x32_bf16 v[14:17], v[134:137], v[232:235], v[14:17]
	v_mfma_f32_16x16x32_bf16 v[10:13], v[142:145], v[232:235], v[10:13]
	s_setprio 0
	s_setprio 1
	v_mfma_f32_16x16x32_bf16 v[54:57], v[146:149], v[186:189], v[54:57]
	v_mfma_f32_16x16x32_bf16 v[50:53], v[154:157], v[186:189], v[50:53]
	v_mfma_f32_16x16x32_bf16 v[38:41], v[146:149], v[194:197], v[38:41]
	v_mfma_f32_16x16x32_bf16 v[34:37], v[154:157], v[194:197], v[34:37]
	v_mfma_f32_16x16x32_bf16 v[22:25], v[146:149], v[220:223], v[22:25]
	v_mfma_f32_16x16x32_bf16 v[18:21], v[154:157], v[220:223], v[18:21]
	v_mfma_f32_16x16x32_bf16 v[6:9], v[146:149], v[228:231], v[6:9]
	v_mfma_f32_16x16x32_bf16 v[2:5], v[154:157], v[228:231], v[2:5]
	v_mfma_f32_16x16x32_bf16 v[54:57], v[150:153], v[190:193], v[54:57]
	v_mfma_f32_16x16x32_bf16 v[50:53], v[182:185], v[190:193], v[50:53]
	v_mfma_f32_16x16x32_bf16 v[38:41], v[150:153], v[216:219], v[38:41]
	v_mfma_f32_16x16x32_bf16 v[34:37], v[182:185], v[216:219], v[34:37]
	v_mfma_f32_16x16x32_bf16 v[22:25], v[150:153], v[224:227], v[22:25]
	v_mfma_f32_16x16x32_bf16 v[18:21], v[182:185], v[224:227], v[18:21]
	v_mfma_f32_16x16x32_bf16 v[6:9], v[150:153], v[232:235], v[6:9]
	v_mfma_f32_16x16x32_bf16 v[2:5], v[182:185], v[232:235], v[2:5]
	s_setprio 0
	s_barrier
; #define PG8_STAGE(bufoff, gbase, voff) do { _Pragma("unroll") for (int _i = 0; _i < 2; ++_i) \
;         __builtin_amdgcn_global_load_lds((const unsigned*)((const char*)(gbase) + (voff)[_i]), (PG8_LAS unsigned*)(lds + (bufoff) + ldsw + _i * 8192), 16, 0, 0); } while (0)
; #define PG8_LDA(dst, b, h) do { _Pragma("unroll") for (int m = 0; m < 4; ++m) _Pragma("unroll") for (int k = 0; k < 2; ++k) dst[m][k] = *(const PG8_LAS bf16x8*)(lds + PG8_SA(b, h) + aoff + m * 2048 + k * 1024); } while (0)
; #define PG8_LDB(dst, b, h) do { _Pragma("unroll") for (int n = 0; n < 2; ++n) _Pragma("unroll") for (int k = 0; k < 2; ++k) dst[n][k] = *(const PG8_LAS bf16x8*)(lds + PG8_SB(b, h) + boff + n * 2048 + k * 1024); } while (0)
; #define PG8_MMA(ai, bj, At, Bt) do { __builtin_amdgcn_s_setprio(1); _Pragma("unroll") for (int m = 0; m < 4; ++m) _Pragma("unroll") for (int n = 0; n < 2; ++n) _Pragma("unroll") for (int k = 0; k < 2; ++k) \
;         acc[ai][bj][m][n] = __builtin_amdgcn_mfma_f32_16x16x32_bf16(Bt[n][k], At[m][k], acc[ai][bj][m][n], 0, 0, 0); __builtin_amdgcn_s_setprio(0); } while (0)
; #define PG8_WAIT_V(n) asm volatile("s_waitcnt vmcnt(" #n ")" ::: "memory")
; #define PG8_WAIT_L(n) asm volatile("s_waitcnt lgkmcnt(" #n ")" ::: "memory")
; #define PG8_BAR __builtin_amdgcn_s_barrier()
; #define PG8_SCHED __builtin_amdgcn_sched_barrier(0)
; template <class Epi, class Sched, bool ALIGN_EPI = false, bool SP2 = false>
; __device__ __forceinline__ void gemm_phase(PG8_LAS unsigned char* lds, const Gemm g, const Sched& S, const Epi& E) {
;     ...
;             PG8_LDA(At, 0, 1); PG8_STAGE(PG8_SB(0, 0), b2, voffB); PG8_STAGE(PG8_SB(0, 1), b2 + hstep, voffB); PG8_STAGE(PG8_SA(0, 0), a2, voffA);
;             PG8_WAIT_V(8); PG8_WAIT_L(0); PG8_BAR; PG8_MMA(1, 0, At, B0); PG8_MMA(1, 1, At, B1); PG8_BAR; PG8_SCHED;
;             PG8_LDB(B0, 1, 0); PG8_LDB(B1, 1, 1); PG8_SCHED; PG8_LDA(At, 1, 0); PG8_STAGE(PG8_SA(0, 1), a2 + hstep, voffA);
;             PG8_WAIT_V(8); PG8_WAIT_L(0); PG8_BAR; PG8_MMA(0, 0, At, B0); PG8_MMA(0, 1, At, B1); PG8_BAR; PG8_SCHED;
;             PG8_LDA(At, 1, 1); PG8_STAGE(PG8_SB(1, 0), b3, voffB); PG8_STAGE(PG8_SB(1, 1), b3 + hstep, voffB); PG8_STAGE(PG8_SA(1, 0), a3, voffA);
;             PG8_WAIT_V(8); PG8_WAIT_L(0); PG8_BAR; PG8_MMA(1, 0, At, B0); PG8_MMA(1, 1, At, B1); PG8_BAR; PG8_SCHED;
	s_add_i32 s50, 0, 0x18000
	s_add_i32 s51, 0, 0x1c000
	v_add_u32_e32 v142, s50, v165
	v_add_u32_e32 v182, s51, v165
	ds_read_b128 v[130:133], v142
	ds_read_b128 v[134:137], v142 offset:1024
	ds_read_b128 v[138:141], v142 offset:2048
	ds_read_b128 v[142:145], v142 offset:3072
	ds_read_b128 v[146:149], v182
	ds_read_b128 v[150:153], v182 offset:1024
	ds_read_b128 v[154:157], v182 offset:2048
	ds_read_b128 v[182:185], v182 offset:3072
	s_add_u32 s18, s24, 0xb0000
	s_addc_u32 s19, s25, 0
	s_mov_b32 m0, s30
	ds_read_b128 v[186:189], v214 offset:32768
	ds_read_b128 v[190:193], v214 offset:33792
	ds_read_b128 v[194:197], v214 offset:34816
	ds_read_b128 v[216:219], v214 offset:35840
	ds_read_b128 v[220:223], v214 offset:36864
	ds_read_b128 v[224:227], v214 offset:37888
	ds_read_b128 v[228:231], v214 offset:38912
	ds_read_b128 v[232:235], v214 offset:39936
	global_load_lds_dwordx4 v176, s[18:19]
	s_mov_b32 m0, s31
	s_nop 0
	global_load_lds_dwordx4 v174, s[18:19]
	s_waitcnt vmcnt(8)
	s_waitcnt lgkmcnt(0)
	s_barrier
	s_setprio 1
	s_waitcnt lgkmcnt(0)
	v_mfma_f32_16x16x32_bf16 v[126:129], v[130:133], v[186:189], v[126:129]
	v_mfma_f32_16x16x32_bf16 v[122:125], v[138:141], v[186:189], v[122:125]
	v_mfma_f32_16x16x32_bf16 v[110:113], v[130:133], v[194:197], v[110:113]
	v_mfma_f32_16x16x32_bf16 v[106:109], v[138:141], v[194:197], v[106:109]
	v_mfma_f32_16x16x32_bf16 v[94:97], v[130:133], v[220:223], v[94:97]
	v_mfma_f32_16x16x32_bf16 v[90:93], v[138:141], v[220:223], v[90:93]
	v_mfma_f32_16x16x32_bf16 v[78:81], v[130:133], v[228:231], v[78:81]
	v_mfma_f32_16x16x32_bf16 v[74:77], v[138:141], v[228:231], v[74:77]
	v_mfma_f32_16x16x32_bf16 v[126:129], v[134:137], v[190:193], v[126:129]
	v_mfma_f32_16x16x32_bf16 v[122:125], v[142:145], v[190:193], v[122:125]
	v_mfma_f32_16x16x32_bf16 v[110:113], v[134:137], v[216:219], v[110:113]
	v_mfma_f32_16x16x32_bf16 v[106:109], v[142:145], v[216:219], v[106:109]
	v_mfma_f32_16x16x32_bf16 v[94:97], v[134:137], v[224:227], v[94:97]
	v_mfma_f32_16x16x32_bf16 v[90:93], v[142:145], v[224:227], v[90:93]
	v_mfma_f32_16x16x32_bf16 v[78:81], v[134:137], v[232:235], v[78:81]
	v_mfma_f32_16x16x32_bf16 v[74:77], v[142:145], v[232:235], v[74:77]
	s_setprio 0
	s_setprio 1
	v_mfma_f32_16x16x32_bf16 v[118:121], v[146:149], v[186:189], v[118:121]
	v_mfma_f32_16x16x32_bf16 v[114:117], v[154:157], v[186:189], v[114:117]
	v_mfma_f32_16x16x32_bf16 v[102:105], v[146:149], v[194:197], v[102:105]
	v_mfma_f32_16x16x32_bf16 v[98:101], v[154:157], v[194:197], v[98:101]
	v_mfma_f32_16x16x32_bf16 v[86:89], v[146:149], v[220:223], v[86:89]
	v_mfma_f32_16x16x32_bf16 v[82:85], v[154:157], v[220:223], v[82:85]
	v_mfma_f32_16x16x32_bf16 v[70:73], v[146:149], v[228:231], v[70:73]
	v_mfma_f32_16x16x32_bf16 v[66:69], v[154:157], v[228:231], v[66:69]
	v_mfma_f32_16x16x32_bf16 v[118:121], v[150:153], v[190:193], v[118:121]
	v_mfma_f32_16x16x32_bf16 v[114:117], v[182:185], v[190:193], v[114:117]
	v_mfma_f32_16x16x32_bf16 v[102:105], v[150:153], v[216:219], v[102:105]
	v_mfma_f32_16x16x32_bf16 v[98:101], v[182:185], v[216:219], v[98:101]
	v_mfma_f32_16x16x32_bf16 v[86:89], v[150:153], v[224:227], v[86:89]
	v_mfma_f32_16x16x32_bf16 v[82:85], v[182:185], v[224:227], v[82:85]
	v_mfma_f32_16x16x32_bf16 v[70:73], v[150:153], v[232:235], v[70:73]
	v_mfma_f32_16x16x32_bf16 v[66:69], v[182:185], v[232:235], v[66:69]
	s_setprio 0
	s_barrier
	s_add_i32 s18, s50, s2
	s_add_u32 s98, s22, 0x80
	s_addc_u32 s99, s23, 0
	s_add_u32 s100, s24, 0x80
	s_addc_u32 s101, s25, 0
	s_mov_b32 m0, s18
	ds_read_b128 v[186:189], v214 offset:49152
	ds_read_b128 v[190:193], v214 offset:50176
	ds_read_b128 v[194:197], v214 offset:51200
	ds_read_b128 v[216:219], v214 offset:52224
	ds_read_b128 v[220:223], v214 offset:53248
	ds_read_b128 v[224:227], v214 offset:54272
	ds_read_b128 v[228:231], v214 offset:55296
	ds_read_b128 v[232:235], v214 offset:56320
	global_load_lds_dwordx4 v0, s[98:99]
	s_add_i32 m0, s18, 0x2000
	s_add_u32 s18, s22, 0xb0080
	s_addc_u32 s19, s23, 0
	s_add_i32 s22, s51, s2
	global_load_lds_dwordx4 v172, s[98:99]
	s_mov_b32 m0, s22
	s_nop 0
	global_load_lds_dwordx4 v0, s[18:19]
	s_add_i32 m0, s22, 0x2000
	s_nop 0
	global_load_lds_dwordx4 v172, s[18:19]
	s_mov_b32 m0, s35
	s_nop 0
	global_load_lds_dwordx4 v176, s[100:101]
	s_mov_b32 m0, s37
	s_nop 0
	global_load_lds_dwordx4 v174, s[100:101]
	s_waitcnt vmcnt(8)
	s_waitcnt lgkmcnt(0)
	s_barrier
; #define PG8_STAGE(bufoff, gbase, voff) do { _Pragma("unroll") for (int _i = 0; _i < 2; ++_i) \
;         __builtin_amdgcn_global_load_lds((const unsigned*)((const char*)(gbase) + (voff)[_i]), (PG8_LAS unsigned*)(lds + (bufoff) + ldsw + _i * 8192), 16, 0, 0); } while (0)
; template <class Epi, class Sched, bool ALIGN_EPI = false, bool SP2 = false>
; __device__ __forceinline__ void gemm_phase(PG8_LAS unsigned char* lds, const Gemm g, const Sched& S, const Epi& E) {
;     ...
;             PG8_WAIT_V(8); PG8_WAIT_L(0); PG8_BAR; PG8_MMA(1, 0, At, B0); PG8_MMA(1, 1, At, B1); PG8_BAR; PG8_SCHED;
;             } else {
;             PG8_LDB(B0, 0, 0); PG8_SCHED; PG8_LDA(At, 0, 0); PG8_STAGE(PG8_SA(1, 1), a1 + hstep, voffA);
;             PG8_WAIT_L(8); PG8_BAR; PG8_WAIT_L(0); PG8_MMA(0, 0, At, B0); PG8_BAR; PG8_SCHED;
;             PG8_LDB(B1, 0, 1); PG8_STAGE(PG8_SB(0, 0), b2, voffB);
;             PG8_BAR; PG8_WAIT_L(0); PG8_MMA(0, 1, At, B1); PG8_BAR;
;             PG8_LDA(At, 0, 1); PG8_STAGE(PG8_SA(0, 0), a2, voffA);
;             PG8_BAR; PG8_WAIT_L(0); PG8_MMA(1, 0, At, B0); PG8_BAR; PG8_SCHED;
;             PG8_STAGE(PG8_SB(0, 1), b2 + hstep, voffB);
;             PG8_WAIT_V(6); PG8_BAR; PG8_MMA(1, 1, At, B1); PG8_BAR;
;             PG8_LDB(B0, 1, 0); PG8_SCHED; PG8_LDA(At, 1, 0); PG8_STAGE(PG8_SA(0, 1), a2 + hstep, voffA);
;             PG8_WAIT_L(8); PG8_BAR; PG8_WAIT_L(0); PG8_MMA(0, 0, At, B0); PG8_BAR; PG8_SCHED;
;             PG8_LDB(B1, 1, 1); PG8_STAGE(PG8_SB(1, 0), b3, voffB);
;             PG8_BAR; PG8_WAIT_L(0); PG8_MMA(0, 1, At, B1); PG8_BAR;
;             PG8_LDA(At, 1, 1); PG8_STAGE(PG8_SA(1, 0), a3, voffA);
;             PG8_BAR; PG8_WAIT_L(0); PG8_MMA(1, 0, At, B0); PG8_BAR; PG8_SCHED;
;             PG8_STAGE(PG8_SB(1, 1), b3 + hstep, voffB);
;             PG8_WAIT_V(6); PG8_BAR; PG8_MMA(1, 1, At, B1); PG8_BAR;
;             }
;         }
;         if constexpr (ALIGN_EPI) { if (wr == 0) PG8_BAR; }
;     __device__ __forceinline__ void operator()(const f32x4 (&acc)[2][2][4][2], const Unit& u, int wr, int wc, int fr, int fq) const {
;     ...
; #pragma unroll
;         for (int ai = 0; ai < 2; ++ai) {
;             u32x4 xv[4][2];
; #pragma unroll
;             for (int m = 0; m < 4; ++m)
; #pragma unroll
;                 for (int bj = 0; bj < 2; ++bj) xv[m][bj] = *(const u32x4*)(XB + (size_t)(row0 + ai * HALF + m * 16) * 1024 + col0 + bj * HALF);
	s_setprio 1
	s_waitcnt lgkmcnt(0)
	v_mfma_f32_16x16x32_bf16 v[62:65], v[130:133], v[186:189], v[62:65]
	v_mfma_f32_16x16x32_bf16 v[58:61], v[138:141], v[186:189], v[58:61]
	v_mfma_f32_16x16x32_bf16 v[46:49], v[130:133], v[194:197], v[46:49]
	v_mfma_f32_16x16x32_bf16 v[42:45], v[138:141], v[194:197], v[42:45]
	v_mfma_f32_16x16x32_bf16 v[30:33], v[130:133], v[220:223], v[30:33]
	v_mfma_f32_16x16x32_bf16 v[26:29], v[138:141], v[220:223], v[26:29]
	v_mfma_f32_16x16x32_bf16 v[14:17], v[130:133], v[228:231], v[14:17]
	v_mfma_f32_16x16x32_bf16 v[10:13], v[138:141], v[228:231], v[10:13]
	v_mfma_f32_16x16x32_bf16 v[62:65], v[134:137], v[190:193], v[62:65]
	v_mfma_f32_16x16x32_bf16 v[58:61], v[142:145], v[190:193], v[58:61]
	v_mfma_f32_16x16x32_bf16 v[46:49], v[134:137], v[216:219], v[46:49]
	v_mfma_f32_16x16x32_bf16 v[42:45], v[142:145], v[216:219], v[42:45]
	v_mfma_f32_16x16x32_bf16 v[30:33], v[134:137], v[224:227], v[30:33]
	v_mfma_f32_16x16x32_bf16 v[26:29], v[142:145], v[224:227], v[26:29]
	v_mfma_f32_16x16x32_bf16 v[14:17], v[134:137], v[232:235], v[14:17]
	v_mfma_f32_16x16x32_bf16 v[10:13], v[142:145], v[232:235], v[10:13]
	s_setprio 0
	s_setprio 1
	v_mfma_f32_16x16x32_bf16 v[54:57], v[146:149], v[186:189], v[54:57]
	v_mfma_f32_16x16x32_bf16 v[50:53], v[154:157], v[186:189], v[50:53]
	v_mfma_f32_16x16x32_bf16 v[38:41], v[146:149], v[194:197], v[38:41]
	v_mfma_f32_16x16x32_bf16 v[34:37], v[154:157], v[194:197], v[34:37]
	v_mfma_f32_16x16x32_bf16 v[22:25], v[146:149], v[220:223], v[22:25]
	v_mfma_f32_16x16x32_bf16 v[18:21], v[154:157], v[220:223], v[18:21]
	v_mfma_f32_16x16x32_bf16 v[6:9], v[146:149], v[228:231], v[6:9]
	v_mfma_f32_16x16x32_bf16 v[2:5], v[154:157], v[228:231], v[2:5]
	v_mfma_f32_16x16x32_bf16 v[54:57], v[150:153], v[190:193], v[54:57]
	v_mfma_f32_16x16x32_bf16 v[50:53], v[182:185], v[190:193], v[50:53]
	v_mfma_f32_16x16x32_bf16 v[38:41], v[150:153], v[216:219], v[38:41]
	v_mfma_f32_16x16x32_bf16 v[34:37], v[182:185], v[216:219], v[34:37]
	v_mfma_f32_16x16x32_bf16 v[22:25], v[150:153], v[224:227], v[22:25]
	v_mfma_f32_16x16x32_bf16 v[18:21], v[182:185], v[224:227], v[18:21]
	v_mfma_f32_16x16x32_bf16 v[6:9], v[150:153], v[232:235], v[6:9]
	v_mfma_f32_16x16x32_bf16 v[2:5], v[182:185], v[232:235], v[2:5]
	s_setprio 0
	s_barrier
	s_add_i32 s49, s49, 2
	s_add_u32 s47, s47, 0x100
	s_addc_u32 s48, s48, 0
	s_cmp_gt_u32 s49, 41
	s_mov_b64 s[18:19], s[20:21]
	s_cbranch_scc0 .LBB0_459
	v_lshl_or_b32 v198, s45, 8, v213
	v_lshl_add_u32 v217, s46, 8, v158
	v_lshlrev_b32_e32 v246, 1, v198
	v_lshl_add_u32 v246, v217, 11, v246
	v_mov_b32_e32 v247, 0
	s_mov_b32 s18, 0x8000
	s_mov_b32 s19, 0
	s_mov_b32 s88, 0x28000
	v_lshl_add_u64 v[246:247], s[94:95], 0, v[246:247]
	v_xor_b32_e32 v215, 16, v201
	v_xor_b32_e32 v216, 32, v201
	v_mov_b32_e32 v198, v246
	v_mov_b32_e32 v199, v247
	global_load_dwordx4 v[130:133], v[246:247], off
	global_load_dwordx4 v[134:137], v[246:247], off offset:256
	v_lshl_add_u64 v[246:247], v[246:247], 0, s[18:19]
	global_load_dwordx4 v[138:141], v[246:247], off
	global_load_dwordx4 v[142:145], v[246:247], off offset:256
	v_lshl_add_u64 v[246:247], v[246:247], 0, s[18:19]
	global_load_dwordx4 v[146:149], v[246:247], off
	global_load_dwordx4 v[150:153], v[246:247], off offset:256
	v_lshl_add_u64 v[246:247], v[246:247], 0, s[18:19]
	global_load_dwordx4 v[154:157], v[246:247], off
	global_load_dwordx4 v[218:221], v[246:247], off offset:256
	v_lshl_add_u64 v[246:247], v[246:247], 0, s[88:89]
	global_load_dwordx4 v[182:185], v[246:247], off
	global_load_dwordx4 v[186:189], v[246:247], off offset:256
	v_lshl_add_u64 v[246:247], v[246:247], 0, s[18:19]
	global_load_dwordx4 v[190:193], v[246:247], off
	global_load_dwordx4 v[194:197], v[246:247], off offset:256
	v_lshl_add_u64 v[246:247], v[246:247], 0, s[18:19]
	global_load_dwordx4 v[222:225], v[246:247], off
	global_load_dwordx4 v[226:229], v[246:247], off offset:256
	v_lshl_add_u64 v[246:247], v[246:247], 0, s[18:19]
	global_load_dwordx4 v[230:233], v[246:247], off
	global_load_dwordx4 v[234:237], v[246:247], off offset:256
	v_lshlrev_b32_e32 v215, 2, v215
	v_lshlrev_b32_e32 v216, 2, v216
	s_and_b64 vcc, exec, s[14:15]
	s_cbranch_vccz .LBB0_462
	s_barrier
